# v44 with the waves 4-7 barrier moved behind the P.V MFMAs (in front of the QK^T chain)
# speedup vs baseline: 1.0299x; 1.0299x over previous
; #define LAS __attribute__((address_space(3)))
; DI void expsum(f32x16& p, float& l_reg, bf16x8& pa0, bf16x8& pa1) {
; #pragma unroll
;     for (int r = 0; r < 16; ++r) p[r] = __builtin_amdgcn_exp2f(p[r]);
;     float ps = 0.f;
; #pragma unroll
;     for (int r = 0; r < 16; ++r) ps += p[r];
;     l_reg += ps; asm volatile("" : "+v"(l_reg));
;     ...
;     ATT_PK4(p, 0, pa0); ATT_PK4(p, 8, pa1);
;     ...
; }
; DI int v_rd_base(int lane) { return ((lane & 3) << 3) | (((lane >> 2) & 3) << 6) | (((lane >> 4) & 1) << 5) | (((lane >> 5) & 1) << 8); }
; template <int OFF> DI s16x4 tr_read(int vb) { s16x4 r; asm volatile("ds_read_b64_tr_b16 %0, %1 offset:%2" : "=&v"(r) : "v"(vb), "i"(OFF) : "memory"); return r; }
; template <int H> DI void v_reads(s16x4* vf, int vb) {
;     vf[0] = tr_read<v_rd_off(0, 2 * H, 0)>(vb); vf[1] = tr_read<v_rd_off(0, 2 * H, 1)>(vb); vf[2] = tr_read<v_rd_off(0, 2 * H + 1, 0)>(vb); vf[3] = tr_read<v_rd_off(0, 2 * H + 1, 1)>(vb);
;     vf[4] = tr_read<v_rd_off(1, 2 * H, 0)>(vb); vf[5] = tr_read<v_rd_off(1, 2 * H, 1)>(vb); vf[6] = tr_read<v_rd_off(1, 2 * H + 1, 0)>(vb); vf[7] = tr_read<v_rd_off(1, 2 * H + 1, 1)>(vb);
;     vf[8] = tr_read<v_rd_off(2, 2 * H, 0)>(vb); vf[9] = tr_read<v_rd_off(2, 2 * H, 1)>(vb); vf[10] = tr_read<v_rd_off(2, 2 * H + 1, 0)>(vb); vf[11] = tr_read<v_rd_off(2, 2 * H + 1, 1)>(vb);
;     vf[12] = tr_read<v_rd_off(3, 2 * H, 0)>(vb); vf[13] = tr_read<v_rd_off(3, 2 * H, 1)>(vb); vf[14] = tr_read<v_rd_off(3, 2 * H + 1, 0)>(vb); vf[15] = tr_read<v_rd_off(3, 2 * H + 1, 1)>(vb);
; }
; DI void pv_mma(f32x16* o, const s16x4* vf, bf16x8 pa0, bf16x8 pa1) {
;     ...
; #pragma unroll
;     for (int d0 = 0; d0 < 4; ++d0) {
;         o[d0] = __builtin_amdgcn_mfma_f32_32x32x16_bf16(pa0, ATT_PK(vf[4 * d0], vf[4 * d0 + 1]), o[d0], 0, 0, 0);
;         o[d0] = __builtin_amdgcn_mfma_f32_32x32x16_bf16(pa1, ATT_PK(vf[4 * d0 + 2], vf[4 * d0 + 3]), o[d0], 0, 0, 0); }
;     ...
; }
; template <int DQK, int D0A, int D0B> DI void k_reads(bf16x8* kf, const LAS unsigned char* Ks, int half, int r32, int hi) {
; #pragma unroll
;     for (int d0 = D0A; d0 < D0B; ++d0) kf[d0 - D0A] = *(const LAS bf16x8*)(Ks + half * (32 * DQK * 2) + kswz<DQK>(r32, (d0 * 16 + hi * 8) * 2));
; }
; template <int D0A, int D0B> DI void qk_mma(f32x16& p, const bf16x8* kf, const bf16x8* qr) {
; #pragma unroll
;     for (int d0 = D0A; d0 < D0B; ++d0) {
.LBB0_1924:
	s_add_i32 s3, s22, 0xffffc000
	s_and_b32 s3, s3, 0x6000
	v_add_u32_e32 v123, s3, v114
	v_add_u32_e32 v140, v123, v118
	v_add_u32_e32 v136, v123, v117
	v_add_u32_e32 v132, v123, v116
	v_add_u32_e32 v123, v123, v115
	ds_read_b128 v[124:127], v123
	ds_read_b128 v[132:135], v132
	ds_read_b128 v[136:139], v136
	ds_read_b128 v[140:143], v140
	ds_read_b64_tr_b16 v[144:145], v121 offset:0x2000
	ds_read_b64_tr_b16 v[146:147], v121 offset:0x2800
	ds_read_b64_tr_b16 v[148:149], v121 offset:0x3000
	ds_read_b64_tr_b16 v[150:151], v121 offset:0x3800
	ds_read_b64_tr_b16 v[152:153], v121 offset:0x2200
	ds_read_b64_tr_b16 v[154:155], v121 offset:0x2a00
	ds_read_b64_tr_b16 v[156:157], v121 offset:0x3200
	ds_read_b64_tr_b16 v[158:159], v121 offset:0x3a00
	ds_read_b64_tr_b16 v[162:163], v121 offset:0x2400
	ds_read_b64_tr_b16 v[164:165], v121 offset:0x2c00
	ds_read_b64_tr_b16 v[166:167], v121 offset:0x3400
	ds_read_b64_tr_b16 v[168:169], v121 offset:0x3c00
	ds_read_b64_tr_b16 v[170:171], v121 offset:0x2600
	ds_read_b64_tr_b16 v[172:173], v121 offset:0x2e00
	ds_read_b64_tr_b16 v[174:175], v121 offset:0x3600
	ds_read_b64_tr_b16 v[176:177], v121 offset:0x3e00
	s_setprio 2
	v_exp_f32_e32 v64, v64
	v_exp_f32_e32 v65, v65
	v_exp_f32_e32 v66, v66
	v_exp_f32_e32 v67, v67
	v_exp_f32_e32 v68, v68
	v_add_f32_e32 v121, 0, v64
	v_exp_f32_e32 v69, v69
	v_add_f32_e32 v121, v65, v121
	v_exp_f32_e32 v70, v70
	v_add_f32_e32 v121, v66, v121
	v_exp_f32_e32 v71, v71
	v_add_f32_e32 v121, v67, v121
	v_exp_f32_e32 v72, v72
	v_add_f32_e32 v121, v68, v121
	v_exp_f32_e32 v73, v73
	v_add_f32_e32 v121, v69, v121
	v_exp_f32_e32 v74, v74
	v_add_f32_e32 v121, v70, v121
	v_exp_f32_e32 v75, v75
	v_add_f32_e32 v121, v71, v121
	v_exp_f32_e32 v76, v76
	v_add_f32_e32 v121, v72, v121
	v_exp_f32_e32 v77, v77
	v_add_f32_e32 v121, v73, v121
	v_exp_f32_e32 v78, v78
	v_add_f32_e32 v121, v74, v121
	v_exp_f32_e32 v79, v79
	v_add_f32_e32 v121, v75, v121
	v_add_f32_e32 v121, v76, v121
	v_add_f32_e32 v121, v77, v121
	v_add_f32_e32 v121, v78, v121
	v_add_f32_e32 v121, v79, v121
	v_add_f32_e32 v120, v120, v121
	v_cvt_pk_bf16_f32 v64, v64, v65
	v_cvt_pk_bf16_f32 v65, v66, v67
	v_cvt_pk_bf16_f32 v66, v68, v69
	v_cvt_pk_bf16_f32 v67, v70, v71
	v_cvt_pk_bf16_f32 v68, v72, v73
	v_cvt_pk_bf16_f32 v69, v74, v75
	v_cvt_pk_bf16_f32 v70, v76, v77
	v_cvt_pk_bf16_f32 v71, v78, v79
	s_nop 0
	v_permlane32_swap_b32_e32 v64, v66
	v_permlane32_swap_b32_e32 v65, v67
	v_permlane32_swap_b32_e32 v68, v70
	v_permlane32_swap_b32_e32 v69, v71
	s_waitcnt lgkmcnt(0)
	s_setprio 1
	v_mfma_f32_32x32x16_bf16 v[0:15], v[64:67], v[144:147], v[0:15]
	s_cmp_lt_i32 s0, s55
	s_cselect_b64 s[74:75], -1, 0
	s_cmp_ge_i32 s0, s97
	s_cselect_b64 vcc, -1, 0
	s_or_b64 s[74:75], s[74:75], vcc
	s_and_b64 vcc, exec, s[74:75]
	v_mfma_f32_32x32x16_bf16 v[48:63], v[64:67], v[152:155], v[48:63]
	v_mfma_f32_32x32x16_bf16 v[32:47], v[64:67], v[162:165], v[32:47]
	v_mfma_f32_32x32x16_bf16 v[16:31], v[64:67], v[170:173], v[16:31]
	v_mfma_f32_32x32x16_bf16 v[0:15], v[68:71], v[148:151], v[0:15]
	v_mfma_f32_32x32x16_bf16 v[48:63], v[68:71], v[156:159], v[48:63]
	v_mfma_f32_32x32x16_bf16 v[32:47], v[68:71], v[166:169], v[32:47]
	v_mfma_f32_32x32x16_bf16 v[16:31], v[68:71], v[174:177], v[16:31]
	s_cmp_lt_u32 s33, 0x100
	s_cbranch_scc1 .Lstg_d0_mid_11
	s_waitcnt vmcnt(3)
	s_barrier
.Lstg_d0_mid_11:
	v_mfma_f32_32x32x16_bf16 v[64:79], v[124:127], v[92:95], 0
	v_mfma_f32_32x32x16_bf16 v[64:79], v[132:135], v[88:91], v[64:79]
	v_mfma_f32_32x32x16_bf16 v[64:79], v[136:139], v[84:87], v[64:79]
	v_mfma_f32_32x32x16_bf16 v[64:79], v[140:143], v[80:83], v[64:79]
	s_cbranch_vccnz .LBB0_1926
	v_add_u32_e32 v136, 0x28988, v122
	v_add_u32_e32 v138, 0x289a0, v122
	v_add_u32_e32 v140, 0x289a8, v122
	v_add_u32_e32 v123, 0x289c0, v122
	v_add_u32_e32 v124, 0x289c8, v122
	v_add_u32_e32 v126, 0x289e0, v122
	v_add_u32_e32 v132, 0x289e8, v122
	v_add_u32_e32 v121, 0x28980, v122
	ds_read2_b32 v[122:123], v123 offset1:1
	ds_read2_b32 v[124:125], v124 offset1:1
	ds_read2_b32 v[126:127], v126 offset1:1
	ds_read2_b32 v[132:133], v132 offset1:1
	ds_read2_b32 v[134:135], v121 offset1:1
	ds_read2_b32 v[136:137], v136 offset1:1
	ds_read2_b32 v[138:139], v138 offset1:1
	ds_read2_b32 v[140:141], v140 offset1:1
	s_waitcnt lgkmcnt(0)
	v_pk_add_f32 v[78:79], v[78:79], v[132:133]
	v_pk_add_f32 v[76:77], v[76:77], v[126:127]
	v_pk_add_f32 v[74:75], v[74:75], v[124:125]
	v_pk_add_f32 v[72:73], v[72:73], v[122:123]
	v_pk_add_f32 v[70:71], v[70:71], v[140:141]
	v_pk_add_f32 v[68:69], v[68:69], v[138:139]
	v_pk_add_f32 v[66:67], v[66:67], v[136:137]
	v_pk_add_f32 v[64:65], v[64:65], v[134:135]

; #define LAS __attribute__((address_space(3)))
; DI void expsum(f32x16& p, float& l_reg, bf16x8& pa0, bf16x8& pa1) {
; #pragma unroll
;     for (int r = 0; r < 16; ++r) p[r] = __builtin_amdgcn_exp2f(p[r]);
;     float ps = 0.f;
; #pragma unroll
;     for (int r = 0; r < 16; ++r) ps += p[r];
;     l_reg += ps; asm volatile("" : "+v"(l_reg));
;     ...
;     ATT_PK4(p, 0, pa0); ATT_PK4(p, 8, pa1);
;     ...
; }
; DI int v_rd_base(int lane) { return ((lane & 3) << 3) | (((lane >> 2) & 3) << 6) | (((lane >> 4) & 1) << 5) | (((lane >> 5) & 1) << 8); }
; template <int OFF> DI s16x4 tr_read(int vb) { s16x4 r; asm volatile("ds_read_b64_tr_b16 %0, %1 offset:%2" : "=&v"(r) : "v"(vb), "i"(OFF) : "memory"); return r; }
; template <int H> DI void v_reads(s16x4* vf, int vb) {
;     vf[0] = tr_read<v_rd_off(0, 2 * H, 0)>(vb); vf[1] = tr_read<v_rd_off(0, 2 * H, 1)>(vb); vf[2] = tr_read<v_rd_off(0, 2 * H + 1, 0)>(vb); vf[3] = tr_read<v_rd_off(0, 2 * H + 1, 1)>(vb);
;     vf[4] = tr_read<v_rd_off(1, 2 * H, 0)>(vb); vf[5] = tr_read<v_rd_off(1, 2 * H, 1)>(vb); vf[6] = tr_read<v_rd_off(1, 2 * H + 1, 0)>(vb); vf[7] = tr_read<v_rd_off(1, 2 * H + 1, 1)>(vb);
;     vf[8] = tr_read<v_rd_off(2, 2 * H, 0)>(vb); vf[9] = tr_read<v_rd_off(2, 2 * H, 1)>(vb); vf[10] = tr_read<v_rd_off(2, 2 * H + 1, 0)>(vb); vf[11] = tr_read<v_rd_off(2, 2 * H + 1, 1)>(vb);
;     vf[12] = tr_read<v_rd_off(3, 2 * H, 0)>(vb); vf[13] = tr_read<v_rd_off(3, 2 * H, 1)>(vb); vf[14] = tr_read<v_rd_off(3, 2 * H + 1, 0)>(vb); vf[15] = tr_read<v_rd_off(3, 2 * H + 1, 1)>(vb);
; }
; DI void pv_mma(f32x16* o, const s16x4* vf, bf16x8 pa0, bf16x8 pa1) {
;     ...
; #pragma unroll
;     for (int d0 = 0; d0 < 4; ++d0) {
;         o[d0] = __builtin_amdgcn_mfma_f32_32x32x16_bf16(pa0, ATT_PK(vf[4 * d0], vf[4 * d0 + 1]), o[d0], 0, 0, 0);
;         o[d0] = __builtin_amdgcn_mfma_f32_32x32x16_bf16(pa1, ATT_PK(vf[4 * d0 + 2], vf[4 * d0 + 3]), o[d0], 0, 0, 0); }
;     ...
; }
; template <int DQK, int D0A, int D0B> DI void k_reads(bf16x8* kf, const LAS unsigned char* Ks, int half, int r32, int hi) {
; #pragma unroll
;     for (int d0 = D0A; d0 < D0B; ++d0) kf[d0 - D0A] = *(const LAS bf16x8*)(Ks + half * (32 * DQK * 2) + kswz<DQK>(r32, (d0 * 16 + hi * 8) * 2));
; }
; template <int D0A, int D0B> DI void qk_mma(f32x16& p, const bf16x8* kf, const bf16x8* qr) {
; #pragma unroll
;     for (int d0 = D0A; d0 < D0B; ++d0) {
.LBB0_1932:
	s_movk_i32 s64, 0x70
	ds_read_b128 v[98:101], v107 offset:16384
	ds_read_b128 v[102:105], v108 offset:16384
	ds_read_b128 v[114:117], v109 offset:16384
	ds_read_b128 v[118:121], v110 offset:16384
	ds_read_b64_tr_b16 v[122:123], v96 offset:0x2000
	ds_read_b64_tr_b16 v[124:125], v96 offset:0x2800
	ds_read_b64_tr_b16 v[132:133], v96 offset:0x3000
	ds_read_b64_tr_b16 v[134:135], v96 offset:0x3800
	ds_read_b64_tr_b16 v[136:137], v96 offset:0x2200
	ds_read_b64_tr_b16 v[138:139], v96 offset:0x2a00
	ds_read_b64_tr_b16 v[140:141], v96 offset:0x3200
	ds_read_b64_tr_b16 v[142:143], v96 offset:0x3a00
	ds_read_b64_tr_b16 v[144:145], v96 offset:0x2400
	ds_read_b64_tr_b16 v[146:147], v96 offset:0x2c00
	ds_read_b64_tr_b16 v[148:149], v96 offset:0x3400
	ds_read_b64_tr_b16 v[150:151], v96 offset:0x3c00
	ds_read_b64_tr_b16 v[152:153], v96 offset:0x2600
	ds_read_b64_tr_b16 v[154:155], v96 offset:0x2e00
	ds_read_b64_tr_b16 v[156:157], v96 offset:0x3600
	ds_read_b64_tr_b16 v[158:159], v96 offset:0x3e00
	s_nop 5
	s_setprio 2
	v_exp_f32_e32 v64, v64
	v_exp_f32_e32 v65, v65
	v_exp_f32_e32 v66, v66
	v_exp_f32_e32 v67, v67
	v_exp_f32_e32 v68, v68
	v_add_f32_e32 v96, 0, v64
	v_exp_f32_e32 v69, v69
	v_add_f32_e32 v96, v65, v96
	v_exp_f32_e32 v70, v70
	v_add_f32_e32 v96, v66, v96
	v_exp_f32_e32 v71, v71
	v_add_f32_e32 v96, v67, v96
	v_exp_f32_e32 v72, v72
	v_add_f32_e32 v96, v68, v96
	v_exp_f32_e32 v73, v73
	v_add_f32_e32 v96, v69, v96
	v_exp_f32_e32 v74, v74
	v_add_f32_e32 v96, v70, v96
	v_exp_f32_e32 v75, v75
	v_add_f32_e32 v96, v71, v96
	v_exp_f32_e32 v76, v76
	v_add_f32_e32 v96, v72, v96
	v_exp_f32_e32 v77, v77
	v_add_f32_e32 v96, v73, v96
	v_exp_f32_e32 v78, v78
	v_add_f32_e32 v96, v74, v96
	v_exp_f32_e32 v79, v79
	v_add_f32_e32 v96, v75, v96
	v_add_f32_e32 v96, v76, v96
	v_add_f32_e32 v96, v77, v96
	v_add_f32_e32 v96, v78, v96
	v_add_f32_e32 v96, v79, v96
	v_add_f32_e32 v96, v97, v96
	v_cvt_pk_bf16_f32 v64, v64, v65
	v_cvt_pk_bf16_f32 v65, v66, v67
	v_cvt_pk_bf16_f32 v66, v68, v69
	v_cvt_pk_bf16_f32 v67, v70, v71
	v_cvt_pk_bf16_f32 v68, v72, v73
	v_cvt_pk_bf16_f32 v69, v74, v75
	v_cvt_pk_bf16_f32 v70, v76, v77
	v_cvt_pk_bf16_f32 v71, v78, v79
	s_nop 0
	v_permlane32_swap_b32_e32 v64, v66
	v_permlane32_swap_b32_e32 v65, v67
	v_permlane32_swap_b32_e32 v68, v70
	v_permlane32_swap_b32_e32 v69, v71
	s_waitcnt lgkmcnt(0)
	s_setprio 1
	v_mfma_f32_32x32x16_bf16 v[0:15], v[64:67], v[122:125], v[0:15]
	s_cmp_lt_i32 s55, 63
	s_cselect_b64 s[0:1], -1, 0
	s_cmp_gt_i32 s58, 62
	s_cselect_b64 s[2:3], -1, 0
	s_and_b64 s[0:1], s[0:1], s[2:3]
	v_cndmask_b32_e64 v97, 0, 1, s[0:1]
	v_cmp_ne_u32_e64 s[2:3], 1, v97
	v_mfma_f32_32x32x16_bf16 v[48:63], v[64:67], v[136:139], v[48:63]
	v_sub_u32_e32 v97, 0xf80, v111
	s_andn2_b64 vcc, exec, s[0:1]
	v_lshlrev_b32_e32 v97, 2, v97
	v_mfma_f32_32x32x16_bf16 v[32:47], v[64:67], v[144:147], v[32:47]
	v_mfma_f32_32x32x16_bf16 v[16:31], v[64:67], v[152:155], v[16:31]
	v_mfma_f32_32x32x16_bf16 v[0:15], v[68:71], v[132:135], v[0:15]
	v_mfma_f32_32x32x16_bf16 v[48:63], v[68:71], v[140:143], v[48:63]
	v_mfma_f32_32x32x16_bf16 v[32:47], v[68:71], v[148:151], v[32:47]
	v_mfma_f32_32x32x16_bf16 v[16:31], v[68:71], v[156:159], v[16:31]
	s_cmp_lt_u32 s33, 0x100
	s_cbranch_scc1 .Lstg_d0_m61_13
	s_waitcnt vmcnt(0)
	s_barrier
.Lstg_d0_m61_13:
	s_waitcnt lgkmcnt(0)
	v_mfma_f32_32x32x16_bf16 v[64:79], v[98:101], v[92:95], 0
	v_mfma_f32_32x32x16_bf16 v[64:79], v[102:105], v[88:91], v[64:79]
	v_mfma_f32_32x32x16_bf16 v[64:79], v[114:117], v[84:87], v[64:79]
	v_mfma_f32_32x32x16_bf16 v[64:79], v[118:121], v[80:83], v[64:79]
	s_cbranch_vccnz .LBB0_1934
	v_add3_u32 v120, s88, v97, v130
	ds_read2_b32 v[98:99], v120 offset0:240 offset1:241
	ds_read2_b32 v[100:101], v120 offset0:242 offset1:243
	ds_read2_b32 v[102:103], v120 offset0:248 offset1:249
	ds_read2_b32 v[104:105], v120 offset0:250 offset1:251
	ds_read2_b32 v[114:115], v120 offset0:224 offset1:225
	ds_read2_b32 v[116:117], v120 offset0:226 offset1:227
	ds_read2_b32 v[118:119], v120 offset0:232 offset1:233
	ds_read2_b32 v[120:121], v120 offset0:234 offset1:235
	s_waitcnt lgkmcnt(0)
	s_nop 0
	v_pk_add_f32 v[78:79], v[78:79], v[104:105]
	v_pk_add_f32 v[76:77], v[76:77], v[102:103]
	v_pk_add_f32 v[74:75], v[74:75], v[100:101]
	v_pk_add_f32 v[72:73], v[72:73], v[98:99]
	v_pk_add_f32 v[70:71], v[70:71], v[120:121]
	v_pk_add_f32 v[68:69], v[68:69], v[118:119]
	v_pk_add_f32 v[66:67], v[66:67], v[116:117]
	v_pk_add_f32 v[64:65], v[64:65], v[114:115]

; #define LAS __attribute__((address_space(3)))
; DI void expsum(f32x16& p, float& l_reg, bf16x8& pa0, bf16x8& pa1) {
; #pragma unroll
;     for (int r = 0; r < 16; ++r) p[r] = __builtin_amdgcn_exp2f(p[r]);
;     float ps = 0.f;
; #pragma unroll
;     for (int r = 0; r < 16; ++r) ps += p[r];
;     l_reg += ps; asm volatile("" : "+v"(l_reg));
;     ...
;     ATT_PK4(p, 0, pa0); ATT_PK4(p, 8, pa1);
;     ...
; }
; DI int v_rd_base(int lane) { return ((lane & 3) << 3) | (((lane >> 2) & 3) << 6) | (((lane >> 4) & 1) << 5) | (((lane >> 5) & 1) << 8); }
; template <int OFF> DI s16x4 tr_read(int vb) { s16x4 r; asm volatile("ds_read_b64_tr_b16 %0, %1 offset:%2" : "=&v"(r) : "v"(vb), "i"(OFF) : "memory"); return r; }
; template <int H> DI void v_reads(s16x4* vf, int vb) {
;     vf[0] = tr_read<v_rd_off(0, 2 * H, 0)>(vb); vf[1] = tr_read<v_rd_off(0, 2 * H, 1)>(vb); vf[2] = tr_read<v_rd_off(0, 2 * H + 1, 0)>(vb); vf[3] = tr_read<v_rd_off(0, 2 * H + 1, 1)>(vb);
;     vf[4] = tr_read<v_rd_off(1, 2 * H, 0)>(vb); vf[5] = tr_read<v_rd_off(1, 2 * H, 1)>(vb); vf[6] = tr_read<v_rd_off(1, 2 * H + 1, 0)>(vb); vf[7] = tr_read<v_rd_off(1, 2 * H + 1, 1)>(vb);
;     vf[8] = tr_read<v_rd_off(2, 2 * H, 0)>(vb); vf[9] = tr_read<v_rd_off(2, 2 * H, 1)>(vb); vf[10] = tr_read<v_rd_off(2, 2 * H + 1, 0)>(vb); vf[11] = tr_read<v_rd_off(2, 2 * H + 1, 1)>(vb);
;     vf[12] = tr_read<v_rd_off(3, 2 * H, 0)>(vb); vf[13] = tr_read<v_rd_off(3, 2 * H, 1)>(vb); vf[14] = tr_read<v_rd_off(3, 2 * H + 1, 0)>(vb); vf[15] = tr_read<v_rd_off(3, 2 * H + 1, 1)>(vb);
; }
; DI void pv_mma(f32x16* o, const s16x4* vf, bf16x8 pa0, bf16x8 pa1) {
;     ...
; #pragma unroll
;     for (int d0 = 0; d0 < 4; ++d0) {
;         o[d0] = __builtin_amdgcn_mfma_f32_32x32x16_bf16(pa0, ATT_PK(vf[4 * d0], vf[4 * d0 + 1]), o[d0], 0, 0, 0);
;         o[d0] = __builtin_amdgcn_mfma_f32_32x32x16_bf16(pa1, ATT_PK(vf[4 * d0 + 2], vf[4 * d0 + 3]), o[d0], 0, 0, 0); }
;     ...
; }
; template <int DQK, int D0A, int D0B> DI void k_reads(bf16x8* kf, const LAS unsigned char* Ks, int half, int r32, int hi) {
; #pragma unroll
;     for (int d0 = D0A; d0 < D0B; ++d0) kf[d0 - D0A] = *(const LAS bf16x8*)(Ks + half * (32 * DQK * 2) + kswz<DQK>(r32, (d0 * 16 + hi * 8) * 2));
; }
; template <int D0A, int D0B> DI void qk_mma(f32x16& p, const bf16x8* kf, const bf16x8* qr) {
; #pragma unroll
;     for (int d0 = D0A; d0 < D0B; ++d0) {
.LBB0_1938:
	ds_read_b128 v[100:103], v107 offset:24576
	ds_read_b128 v[114:117], v108 offset:24576
	ds_read_b128 v[118:121], v109 offset:24576
	ds_read_b128 v[122:125], v110 offset:24576
	ds_read_b64_tr_b16 v[132:133], v98 offset:0x2000
	ds_read_b64_tr_b16 v[134:135], v98 offset:0x2800
	ds_read_b64_tr_b16 v[136:137], v98 offset:0x3000
	ds_read_b64_tr_b16 v[138:139], v98 offset:0x3800
	ds_read_b64_tr_b16 v[140:141], v98 offset:0x2200
	ds_read_b64_tr_b16 v[142:143], v98 offset:0x2a00
	ds_read_b64_tr_b16 v[144:145], v98 offset:0x3200
	ds_read_b64_tr_b16 v[146:147], v98 offset:0x3a00
	ds_read_b64_tr_b16 v[148:149], v98 offset:0x2400
	ds_read_b64_tr_b16 v[150:151], v98 offset:0x2c00
	ds_read_b64_tr_b16 v[152:153], v98 offset:0x3400
	ds_read_b64_tr_b16 v[154:155], v98 offset:0x3c00
	ds_read_b64_tr_b16 v[156:157], v98 offset:0x2600
	ds_read_b64_tr_b16 v[158:159], v98 offset:0x2e00
	ds_read_b64_tr_b16 v[162:163], v98 offset:0x3600
	ds_read_b64_tr_b16 v[164:165], v98 offset:0x3e00
	s_nop 6
	s_setprio 2
	v_exp_f32_e32 v64, v64
	v_exp_f32_e32 v65, v65
	v_exp_f32_e32 v66, v66
	v_exp_f32_e32 v67, v67
	v_exp_f32_e32 v68, v68
	v_add_f32_e32 v97, 0, v64
	v_exp_f32_e32 v69, v69
	v_add_f32_e32 v97, v65, v97
	v_exp_f32_e32 v70, v70
	v_add_f32_e32 v97, v66, v97
	v_exp_f32_e32 v71, v71
	v_add_f32_e32 v97, v67, v97
	v_exp_f32_e32 v72, v72
	v_add_f32_e32 v97, v68, v97
	v_exp_f32_e32 v73, v73
	v_add_f32_e32 v97, v69, v97
	v_exp_f32_e32 v74, v74
	v_add_f32_e32 v97, v70, v97
	v_exp_f32_e32 v75, v75
	v_add_f32_e32 v97, v71, v97
	v_exp_f32_e32 v76, v76
	v_add_f32_e32 v97, v72, v97
	v_exp_f32_e32 v77, v77
	v_add_f32_e32 v97, v73, v97
	v_exp_f32_e32 v78, v78
	v_add_f32_e32 v97, v74, v97
	v_exp_f32_e32 v79, v79
	v_add_f32_e32 v97, v75, v97
	v_add_f32_e32 v97, v76, v97
	v_add_f32_e32 v97, v77, v97
	v_add_f32_e32 v97, v78, v97
	v_add_f32_e32 v97, v79, v97
	v_add_f32_e32 v96, v96, v97
	v_cvt_pk_bf16_f32 v64, v64, v65
	v_cvt_pk_bf16_f32 v65, v66, v67
	v_cvt_pk_bf16_f32 v66, v68, v69
	v_cvt_pk_bf16_f32 v67, v70, v71
	v_cvt_pk_bf16_f32 v68, v72, v73
	v_cvt_pk_bf16_f32 v69, v74, v75
	v_cvt_pk_bf16_f32 v70, v76, v77
	v_cvt_pk_bf16_f32 v71, v78, v79
	s_nop 0
	v_permlane32_swap_b32_e32 v64, v66
	v_permlane32_swap_b32_e32 v65, v67
	v_permlane32_swap_b32_e32 v68, v70
	v_permlane32_swap_b32_e32 v69, v71
	s_waitcnt lgkmcnt(0)
	s_setprio 1
	v_mfma_f32_32x32x16_bf16 v[0:15], v[64:67], v[132:135], v[0:15]
	s_cmp_lt_i32 s55, 64
	s_cselect_b64 s[0:1], -1, 0
	s_cmp_gt_i32 s58, 63
	s_cselect_b64 s[2:3], -1, 0
	s_and_b64 s[0:1], s[2:3], s[0:1]
	v_cndmask_b32_e64 v97, 0, 1, s[0:1]
	v_cmp_ne_u32_e64 s[2:3], 1, v97
	v_mfma_f32_32x32x16_bf16 v[48:63], v[64:67], v[140:143], v[48:63]
	v_sub_u32_e32 v97, 0xfc0, v111
	s_andn2_b64 vcc, exec, s[0:1]
	v_lshlrev_b32_e32 v97, 2, v97
	v_mfma_f32_32x32x16_bf16 v[32:47], v[64:67], v[148:151], v[32:47]
	v_mfma_f32_32x32x16_bf16 v[16:31], v[64:67], v[156:159], v[16:31]
	v_mfma_f32_32x32x16_bf16 v[0:15], v[68:71], v[136:139], v[0:15]
	v_mfma_f32_32x32x16_bf16 v[48:63], v[68:71], v[144:147], v[48:63]
	v_mfma_f32_32x32x16_bf16 v[32:47], v[68:71], v[152:155], v[32:47]
	v_mfma_f32_32x32x16_bf16 v[16:31], v[68:71], v[162:165], v[16:31]
	s_cmp_lt_u32 s33, 0x100
	s_cbranch_scc1 .Lstg_d0_m62_15
	s_waitcnt vmcnt(0)
	s_barrier
.Lstg_d0_m62_15:
	s_waitcnt lgkmcnt(0)
	v_mfma_f32_32x32x16_bf16 v[64:79], v[100:103], v[92:95], 0
	v_mfma_f32_32x32x16_bf16 v[64:79], v[114:117], v[88:91], v[64:79]
	v_mfma_f32_32x32x16_bf16 v[64:79], v[118:121], v[84:87], v[64:79]
	v_mfma_f32_32x32x16_bf16 v[64:79], v[122:125], v[80:83], v[64:79]
	s_cbranch_vccnz .LBB0_1940
	v_add3_u32 v111, s88, v97, v130
	ds_read2_b32 v[98:99], v111 offset0:240 offset1:241
	ds_read2_b32 v[100:101], v111 offset0:242 offset1:243
	ds_read2_b32 v[102:103], v111 offset0:248 offset1:249
	ds_read2_b32 v[104:105], v111 offset0:250 offset1:251
	ds_read2_b32 v[114:115], v111 offset0:224 offset1:225
	ds_read2_b32 v[116:117], v111 offset0:226 offset1:227
	ds_read2_b32 v[118:119], v111 offset0:232 offset1:233
	ds_read2_b32 v[120:121], v111 offset0:234 offset1:235
	s_waitcnt lgkmcnt(0)
	s_nop 0
	v_pk_add_f32 v[78:79], v[78:79], v[104:105]
	v_pk_add_f32 v[76:77], v[76:77], v[102:103]
	v_pk_add_f32 v[74:75], v[74:75], v[100:101]
	v_pk_add_f32 v[72:73], v[72:73], v[98:99]
	v_pk_add_f32 v[70:71], v[70:71], v[120:121]
	v_pk_add_f32 v[68:69], v[68:69], v[118:119]
	v_pk_add_f32 v[66:67], v[66:67], v[116:117]
	v_pk_add_f32 v[64:65], v[64:65], v[114:115]

; #define LAS __attribute__((address_space(3)))
; DI void expsum(f32x16& p, float& l_reg, bf16x8& pa0, bf16x8& pa1) {
; #pragma unroll
;     for (int r = 0; r < 16; ++r) p[r] = __builtin_amdgcn_exp2f(p[r]);
;     float ps = 0.f;
; #pragma unroll
;     for (int r = 0; r < 16; ++r) ps += p[r];
;     l_reg += ps; asm volatile("" : "+v"(l_reg));
;     ...
;     ATT_PK4(p, 0, pa0); ATT_PK4(p, 8, pa1);
;     ...
; }
; DI int v_rd_base(int lane) { return ((lane & 3) << 3) | (((lane >> 2) & 3) << 6) | (((lane >> 4) & 1) << 5) | (((lane >> 5) & 1) << 8); }
; template <int OFF> DI s16x4 tr_read(int vb) { s16x4 r; asm volatile("ds_read_b64_tr_b16 %0, %1 offset:%2" : "=&v"(r) : "v"(vb), "i"(OFF) : "memory"); return r; }
; template <int H> DI void v_reads(s16x4* vf, int vb) {
;     vf[0] = tr_read<v_rd_off(0, 2 * H, 0)>(vb); vf[1] = tr_read<v_rd_off(0, 2 * H, 1)>(vb); vf[2] = tr_read<v_rd_off(0, 2 * H + 1, 0)>(vb); vf[3] = tr_read<v_rd_off(0, 2 * H + 1, 1)>(vb);
;     vf[4] = tr_read<v_rd_off(1, 2 * H, 0)>(vb); vf[5] = tr_read<v_rd_off(1, 2 * H, 1)>(vb); vf[6] = tr_read<v_rd_off(1, 2 * H + 1, 0)>(vb); vf[7] = tr_read<v_rd_off(1, 2 * H + 1, 1)>(vb);
;     vf[8] = tr_read<v_rd_off(2, 2 * H, 0)>(vb); vf[9] = tr_read<v_rd_off(2, 2 * H, 1)>(vb); vf[10] = tr_read<v_rd_off(2, 2 * H + 1, 0)>(vb); vf[11] = tr_read<v_rd_off(2, 2 * H + 1, 1)>(vb);
;     vf[12] = tr_read<v_rd_off(3, 2 * H, 0)>(vb); vf[13] = tr_read<v_rd_off(3, 2 * H, 1)>(vb); vf[14] = tr_read<v_rd_off(3, 2 * H + 1, 0)>(vb); vf[15] = tr_read<v_rd_off(3, 2 * H + 1, 1)>(vb);
; }
; DI void pv_mma(f32x16* o, const s16x4* vf, bf16x8 pa0, bf16x8 pa1) {
;     ...
; #pragma unroll
;     for (int d0 = 0; d0 < 4; ++d0) {
;         o[d0] = __builtin_amdgcn_mfma_f32_32x32x16_bf16(pa0, ATT_PK(vf[4 * d0], vf[4 * d0 + 1]), o[d0], 0, 0, 0);
;         o[d0] = __builtin_amdgcn_mfma_f32_32x32x16_bf16(pa1, ATT_PK(vf[4 * d0 + 2], vf[4 * d0 + 3]), o[d0], 0, 0, 0); }
;     ...
; }
; template <int DQK, int D0A, int D0B> DI void k_reads(bf16x8* kf, const LAS unsigned char* Ks, int half, int r32, int hi) {
; #pragma unroll
;     for (int d0 = D0A; d0 < D0B; ++d0) kf[d0 - D0A] = *(const LAS bf16x8*)(Ks + half * (32 * DQK * 2) + kswz<DQK>(r32, (d0 * 16 + hi * 8) * 2));
; }
; template <int D0A, int D0B> DI void qk_mma(f32x16& p, const bf16x8* kf, const bf16x8* qr) {
; #pragma unroll
;     for (int d0 = D0A; d0 < D0B; ++d0) {
.LBB0_1955:
	s_add_i32 s3, s22, 0xffffc000
	s_and_b32 s3, s3, 0x6000
	v_add_u32_e32 v123, s3, v114
	v_add_u32_e32 v140, v123, v118
	v_add_u32_e32 v136, v123, v117
	v_add_u32_e32 v132, v123, v116
	v_add_u32_e32 v123, v123, v115
	ds_read_b128 v[124:127], v123
	ds_read_b128 v[132:135], v132
	ds_read_b128 v[136:139], v136
	ds_read_b128 v[140:143], v140
	ds_read_b64_tr_b16 v[144:145], v121 offset:0x2000
	ds_read_b64_tr_b16 v[146:147], v121 offset:0x2800
	ds_read_b64_tr_b16 v[148:149], v121 offset:0x3000
	ds_read_b64_tr_b16 v[150:151], v121 offset:0x3800
	ds_read_b64_tr_b16 v[152:153], v121 offset:0x2200
	ds_read_b64_tr_b16 v[154:155], v121 offset:0x2a00
	ds_read_b64_tr_b16 v[156:157], v121 offset:0x3200
	ds_read_b64_tr_b16 v[158:159], v121 offset:0x3a00
	ds_read_b64_tr_b16 v[162:163], v121 offset:0x2400
	ds_read_b64_tr_b16 v[164:165], v121 offset:0x2c00
	ds_read_b64_tr_b16 v[166:167], v121 offset:0x3400
	ds_read_b64_tr_b16 v[168:169], v121 offset:0x3c00
	ds_read_b64_tr_b16 v[170:171], v121 offset:0x2600
	ds_read_b64_tr_b16 v[172:173], v121 offset:0x2e00
	ds_read_b64_tr_b16 v[174:175], v121 offset:0x3600
	ds_read_b64_tr_b16 v[176:177], v121 offset:0x3e00
	s_setprio 2
	v_exp_f32_e32 v64, v64
	v_exp_f32_e32 v65, v65
	v_exp_f32_e32 v66, v66
	v_exp_f32_e32 v67, v67
	v_exp_f32_e32 v68, v68
	v_add_f32_e32 v121, 0, v64
	v_exp_f32_e32 v69, v69
	v_add_f32_e32 v121, v65, v121
	v_exp_f32_e32 v70, v70
	v_add_f32_e32 v121, v66, v121
	v_exp_f32_e32 v71, v71
	v_add_f32_e32 v121, v67, v121
	v_exp_f32_e32 v72, v72
	v_add_f32_e32 v121, v68, v121
	v_exp_f32_e32 v73, v73
	v_add_f32_e32 v121, v69, v121
	v_exp_f32_e32 v74, v74
	v_add_f32_e32 v121, v70, v121
	v_exp_f32_e32 v75, v75
	v_add_f32_e32 v121, v71, v121
	v_exp_f32_e32 v76, v76
	v_add_f32_e32 v121, v72, v121
	v_exp_f32_e32 v77, v77
	v_add_f32_e32 v121, v73, v121
	v_exp_f32_e32 v78, v78
	v_add_f32_e32 v121, v74, v121
	v_exp_f32_e32 v79, v79
	v_add_f32_e32 v121, v75, v121
	v_add_f32_e32 v121, v76, v121
	v_add_f32_e32 v121, v77, v121
	v_add_f32_e32 v121, v78, v121
	v_add_f32_e32 v121, v79, v121
	v_add_f32_e32 v120, v120, v121
	v_cvt_pk_bf16_f32 v64, v64, v65
	v_cvt_pk_bf16_f32 v65, v66, v67
	v_cvt_pk_bf16_f32 v66, v68, v69
	v_cvt_pk_bf16_f32 v67, v70, v71
	v_cvt_pk_bf16_f32 v68, v72, v73
	v_cvt_pk_bf16_f32 v69, v74, v75
	v_cvt_pk_bf16_f32 v70, v76, v77
	v_cvt_pk_bf16_f32 v71, v78, v79
	s_nop 0
	v_permlane32_swap_b32_e32 v64, v66
	v_permlane32_swap_b32_e32 v65, v67
	v_permlane32_swap_b32_e32 v68, v70
	v_permlane32_swap_b32_e32 v69, v71
	s_waitcnt lgkmcnt(0)
	s_setprio 1
	v_mfma_f32_32x32x16_bf16 v[0:15], v[64:67], v[144:147], v[0:15]
	s_cmp_lt_i32 s0, s47
	s_cselect_b64 s[74:75], -1, 0
	s_cmp_ge_i32 s0, s52
	s_cselect_b64 s[90:91], -1, 0
	s_or_b64 s[74:75], s[74:75], s[90:91]
	s_and_b64 vcc, exec, s[74:75]
	v_mfma_f32_32x32x16_bf16 v[48:63], v[64:67], v[152:155], v[48:63]
	v_mfma_f32_32x32x16_bf16 v[16:31], v[64:67], v[162:165], v[16:31]
	v_mfma_f32_32x32x16_bf16 v[32:47], v[64:67], v[170:173], v[32:47]
	v_mfma_f32_32x32x16_bf16 v[0:15], v[68:71], v[148:151], v[0:15]
	v_mfma_f32_32x32x16_bf16 v[48:63], v[68:71], v[156:159], v[48:63]
	v_mfma_f32_32x32x16_bf16 v[16:31], v[68:71], v[166:169], v[16:31]
	v_mfma_f32_32x32x16_bf16 v[32:47], v[68:71], v[174:177], v[32:47]
	s_cmp_lt_u32 s33, 0x100
	s_cbranch_scc1 .Lstg_d1_mid_19
	s_waitcnt vmcnt(3)
	s_barrier

; #define LAS __attribute__((address_space(3)))
; DI void expsum(f32x16& p, float& l_reg, bf16x8& pa0, bf16x8& pa1) {
; #pragma unroll
;     for (int r = 0; r < 16; ++r) p[r] = __builtin_amdgcn_exp2f(p[r]);
;     float ps = 0.f;
; #pragma unroll
;     for (int r = 0; r < 16; ++r) ps += p[r];
;     l_reg += ps; asm volatile("" : "+v"(l_reg));
;     ...
;     ATT_PK4(p, 0, pa0); ATT_PK4(p, 8, pa1);
;     ...
; }
; DI int v_rd_base(int lane) { return ((lane & 3) << 3) | (((lane >> 2) & 3) << 6) | (((lane >> 4) & 1) << 5) | (((lane >> 5) & 1) << 8); }
; template <int OFF> DI s16x4 tr_read(int vb) { s16x4 r; asm volatile("ds_read_b64_tr_b16 %0, %1 offset:%2" : "=&v"(r) : "v"(vb), "i"(OFF) : "memory"); return r; }
; template <int H> DI void v_reads(s16x4* vf, int vb) {
;     vf[0] = tr_read<v_rd_off(0, 2 * H, 0)>(vb); vf[1] = tr_read<v_rd_off(0, 2 * H, 1)>(vb); vf[2] = tr_read<v_rd_off(0, 2 * H + 1, 0)>(vb); vf[3] = tr_read<v_rd_off(0, 2 * H + 1, 1)>(vb);
;     vf[4] = tr_read<v_rd_off(1, 2 * H, 0)>(vb); vf[5] = tr_read<v_rd_off(1, 2 * H, 1)>(vb); vf[6] = tr_read<v_rd_off(1, 2 * H + 1, 0)>(vb); vf[7] = tr_read<v_rd_off(1, 2 * H + 1, 1)>(vb);
;     vf[8] = tr_read<v_rd_off(2, 2 * H, 0)>(vb); vf[9] = tr_read<v_rd_off(2, 2 * H, 1)>(vb); vf[10] = tr_read<v_rd_off(2, 2 * H + 1, 0)>(vb); vf[11] = tr_read<v_rd_off(2, 2 * H + 1, 1)>(vb);
;     vf[12] = tr_read<v_rd_off(3, 2 * H, 0)>(vb); vf[13] = tr_read<v_rd_off(3, 2 * H, 1)>(vb); vf[14] = tr_read<v_rd_off(3, 2 * H + 1, 0)>(vb); vf[15] = tr_read<v_rd_off(3, 2 * H + 1, 1)>(vb);
; }
; DI void pv_mma(f32x16* o, const s16x4* vf, bf16x8 pa0, bf16x8 pa1) {
;     ...
; #pragma unroll
;     for (int d0 = 0; d0 < 4; ++d0) {
;         o[d0] = __builtin_amdgcn_mfma_f32_32x32x16_bf16(pa0, ATT_PK(vf[4 * d0], vf[4 * d0 + 1]), o[d0], 0, 0, 0);
;         o[d0] = __builtin_amdgcn_mfma_f32_32x32x16_bf16(pa1, ATT_PK(vf[4 * d0 + 2], vf[4 * d0 + 3]), o[d0], 0, 0, 0); }
;     ...
; }
; template <int DQK, int D0A, int D0B> DI void k_reads(bf16x8* kf, const LAS unsigned char* Ks, int half, int r32, int hi) {
; #pragma unroll
;     for (int d0 = D0A; d0 < D0B; ++d0) kf[d0 - D0A] = *(const LAS bf16x8*)(Ks + half * (32 * DQK * 2) + kswz<DQK>(r32, (d0 * 16 + hi * 8) * 2));
; }
; template <int D0A, int D0B> DI void qk_mma(f32x16& p, const bf16x8* kf, const bf16x8* qr) {
; #pragma unroll
;     for (int d0 = D0A; d0 < D0B; ++d0) {
.LBB0_1963:
	ds_read_b128 v[98:101], v107 offset:16384
	ds_read_b128 v[102:105], v108 offset:16384
	ds_read_b128 v[114:117], v109 offset:16384
	ds_read_b128 v[118:121], v110 offset:16384
	ds_read_b64_tr_b16 v[122:123], v96 offset:0x2000
	ds_read_b64_tr_b16 v[124:125], v96 offset:0x2800
	ds_read_b64_tr_b16 v[132:133], v96 offset:0x3000
	ds_read_b64_tr_b16 v[134:135], v96 offset:0x3800
	ds_read_b64_tr_b16 v[136:137], v96 offset:0x2200
	ds_read_b64_tr_b16 v[138:139], v96 offset:0x2a00
	ds_read_b64_tr_b16 v[140:141], v96 offset:0x3200
	ds_read_b64_tr_b16 v[142:143], v96 offset:0x3a00
	ds_read_b64_tr_b16 v[144:145], v96 offset:0x2400
	ds_read_b64_tr_b16 v[146:147], v96 offset:0x2c00
	ds_read_b64_tr_b16 v[148:149], v96 offset:0x3400
	ds_read_b64_tr_b16 v[150:151], v96 offset:0x3c00
	ds_read_b64_tr_b16 v[152:153], v96 offset:0x2600
	ds_read_b64_tr_b16 v[154:155], v96 offset:0x2e00
	ds_read_b64_tr_b16 v[156:157], v96 offset:0x3600
	ds_read_b64_tr_b16 v[158:159], v96 offset:0x3e00
	s_nop 6
	s_setprio 2
	v_exp_f32_e32 v64, v64
	v_exp_f32_e32 v65, v65
	v_exp_f32_e32 v66, v66
	v_exp_f32_e32 v67, v67
	v_exp_f32_e32 v68, v68
	v_add_f32_e32 v96, 0, v64
	v_exp_f32_e32 v69, v69
	v_add_f32_e32 v96, v65, v96
	v_exp_f32_e32 v70, v70
	v_add_f32_e32 v96, v66, v96
	v_exp_f32_e32 v71, v71
	v_add_f32_e32 v96, v67, v96
	v_exp_f32_e32 v72, v72
	v_add_f32_e32 v96, v68, v96
	v_exp_f32_e32 v73, v73
	v_add_f32_e32 v96, v69, v96
	v_exp_f32_e32 v74, v74
	v_add_f32_e32 v96, v70, v96
	v_exp_f32_e32 v75, v75
	v_add_f32_e32 v96, v71, v96
	v_exp_f32_e32 v76, v76
	v_add_f32_e32 v96, v72, v96
	v_exp_f32_e32 v77, v77
	v_add_f32_e32 v96, v73, v96
	v_exp_f32_e32 v78, v78
	v_add_f32_e32 v96, v74, v96
	v_exp_f32_e32 v79, v79
	v_add_f32_e32 v96, v75, v96
	v_add_f32_e32 v96, v76, v96
	v_add_f32_e32 v96, v77, v96
	v_add_f32_e32 v96, v78, v96
	v_add_f32_e32 v96, v79, v96
	v_add_f32_e32 v96, v97, v96
	v_cvt_pk_bf16_f32 v64, v64, v65
	v_cvt_pk_bf16_f32 v65, v66, v67
	v_cvt_pk_bf16_f32 v66, v68, v69
	v_cvt_pk_bf16_f32 v67, v70, v71
	v_cvt_pk_bf16_f32 v68, v72, v73
	v_cvt_pk_bf16_f32 v69, v74, v75
	v_cvt_pk_bf16_f32 v70, v76, v77
	v_cvt_pk_bf16_f32 v71, v78, v79
	s_nop 0
	v_permlane32_swap_b32_e32 v64, v66
	v_permlane32_swap_b32_e32 v65, v67
	v_permlane32_swap_b32_e32 v68, v70
	v_permlane32_swap_b32_e32 v69, v71
	s_waitcnt lgkmcnt(0)
	s_setprio 1
	v_mfma_f32_32x32x16_bf16 v[0:15], v[64:67], v[122:125], v[0:15]
	s_cmp_lt_i32 s47, 63
	s_cselect_b64 s[0:1], -1, 0
	s_cmp_gt_i32 s45, 62
	s_cselect_b64 s[2:3], -1, 0
	s_and_b64 s[0:1], s[0:1], s[2:3]
	v_cndmask_b32_e64 v97, 0, 1, s[0:1]
	v_cmp_ne_u32_e64 s[2:3], 1, v97
	v_mfma_f32_32x32x16_bf16 v[48:63], v[64:67], v[136:139], v[48:63]
	v_sub_u32_e32 v97, 0xf80, v111
	s_andn2_b64 vcc, exec, s[0:1]
	v_lshlrev_b32_e32 v97, 2, v97
	v_mfma_f32_32x32x16_bf16 v[16:31], v[64:67], v[144:147], v[16:31]
	v_mfma_f32_32x32x16_bf16 v[32:47], v[64:67], v[152:155], v[32:47]
	v_mfma_f32_32x32x16_bf16 v[0:15], v[68:71], v[132:135], v[0:15]
	v_mfma_f32_32x32x16_bf16 v[48:63], v[68:71], v[140:143], v[48:63]
	v_mfma_f32_32x32x16_bf16 v[16:31], v[68:71], v[148:151], v[16:31]
	v_mfma_f32_32x32x16_bf16 v[32:47], v[68:71], v[156:159], v[32:47]
	s_cmp_lt_u32 s33, 0x100
	s_cbranch_scc1 .Lstg_d1_m61_21
	s_waitcnt vmcnt(0)
	s_barrier

; #define LAS __attribute__((address_space(3)))
; DI void expsum(f32x16& p, float& l_reg, bf16x8& pa0, bf16x8& pa1) {
; #pragma unroll
;     for (int r = 0; r < 16; ++r) p[r] = __builtin_amdgcn_exp2f(p[r]);
;     float ps = 0.f;
; #pragma unroll
;     for (int r = 0; r < 16; ++r) ps += p[r];
;     l_reg += ps; asm volatile("" : "+v"(l_reg));
;     ...
;     ATT_PK4(p, 0, pa0); ATT_PK4(p, 8, pa1);
;     ...
; }
; DI int v_rd_base(int lane) { return ((lane & 3) << 3) | (((lane >> 2) & 3) << 6) | (((lane >> 4) & 1) << 5) | (((lane >> 5) & 1) << 8); }
; template <int OFF> DI s16x4 tr_read(int vb) { s16x4 r; asm volatile("ds_read_b64_tr_b16 %0, %1 offset:%2" : "=&v"(r) : "v"(vb), "i"(OFF) : "memory"); return r; }
; template <int H> DI void v_reads(s16x4* vf, int vb) {
;     vf[0] = tr_read<v_rd_off(0, 2 * H, 0)>(vb); vf[1] = tr_read<v_rd_off(0, 2 * H, 1)>(vb); vf[2] = tr_read<v_rd_off(0, 2 * H + 1, 0)>(vb); vf[3] = tr_read<v_rd_off(0, 2 * H + 1, 1)>(vb);
;     vf[4] = tr_read<v_rd_off(1, 2 * H, 0)>(vb); vf[5] = tr_read<v_rd_off(1, 2 * H, 1)>(vb); vf[6] = tr_read<v_rd_off(1, 2 * H + 1, 0)>(vb); vf[7] = tr_read<v_rd_off(1, 2 * H + 1, 1)>(vb);
;     vf[8] = tr_read<v_rd_off(2, 2 * H, 0)>(vb); vf[9] = tr_read<v_rd_off(2, 2 * H, 1)>(vb); vf[10] = tr_read<v_rd_off(2, 2 * H + 1, 0)>(vb); vf[11] = tr_read<v_rd_off(2, 2 * H + 1, 1)>(vb);
;     vf[12] = tr_read<v_rd_off(3, 2 * H, 0)>(vb); vf[13] = tr_read<v_rd_off(3, 2 * H, 1)>(vb); vf[14] = tr_read<v_rd_off(3, 2 * H + 1, 0)>(vb); vf[15] = tr_read<v_rd_off(3, 2 * H + 1, 1)>(vb);
; }
; DI void pv_mma(f32x16* o, const s16x4* vf, bf16x8 pa0, bf16x8 pa1) {
;     ...
; #pragma unroll
;     for (int d0 = 0; d0 < 4; ++d0) {
;         o[d0] = __builtin_amdgcn_mfma_f32_32x32x16_bf16(pa0, ATT_PK(vf[4 * d0], vf[4 * d0 + 1]), o[d0], 0, 0, 0);
;         o[d0] = __builtin_amdgcn_mfma_f32_32x32x16_bf16(pa1, ATT_PK(vf[4 * d0 + 2], vf[4 * d0 + 3]), o[d0], 0, 0, 0); }
;     ...
; }
; template <int DQK, int D0A, int D0B> DI void k_reads(bf16x8* kf, const LAS unsigned char* Ks, int half, int r32, int hi) {
; #pragma unroll
;     for (int d0 = D0A; d0 < D0B; ++d0) kf[d0 - D0A] = *(const LAS bf16x8*)(Ks + half * (32 * DQK * 2) + kswz<DQK>(r32, (d0 * 16 + hi * 8) * 2));
; }
; template <int D0A, int D0B> DI void qk_mma(f32x16& p, const bf16x8* kf, const bf16x8* qr) {
; #pragma unroll
;     for (int d0 = D0A; d0 < D0B; ++d0) {
.LBB0_1969:
	ds_read_b128 v[100:103], v107 offset:24576
	ds_read_b128 v[114:117], v108 offset:24576
	ds_read_b128 v[118:121], v109 offset:24576
	ds_read_b128 v[122:125], v110 offset:24576
	ds_read_b64_tr_b16 v[132:133], v98 offset:0x2000
	ds_read_b64_tr_b16 v[134:135], v98 offset:0x2800
	ds_read_b64_tr_b16 v[136:137], v98 offset:0x3000
	ds_read_b64_tr_b16 v[138:139], v98 offset:0x3800
	ds_read_b64_tr_b16 v[140:141], v98 offset:0x2200
	ds_read_b64_tr_b16 v[142:143], v98 offset:0x2a00
	ds_read_b64_tr_b16 v[144:145], v98 offset:0x3200
	ds_read_b64_tr_b16 v[146:147], v98 offset:0x3a00
	ds_read_b64_tr_b16 v[148:149], v98 offset:0x2400
	ds_read_b64_tr_b16 v[150:151], v98 offset:0x2c00
	ds_read_b64_tr_b16 v[152:153], v98 offset:0x3400
	ds_read_b64_tr_b16 v[154:155], v98 offset:0x3c00
	ds_read_b64_tr_b16 v[156:157], v98 offset:0x2600
	ds_read_b64_tr_b16 v[158:159], v98 offset:0x2e00
	ds_read_b64_tr_b16 v[162:163], v98 offset:0x3600
	ds_read_b64_tr_b16 v[164:165], v98 offset:0x3e00
	s_nop 6
	s_setprio 2
	v_exp_f32_e32 v64, v64
	v_exp_f32_e32 v65, v65
	v_exp_f32_e32 v66, v66
	v_exp_f32_e32 v67, v67
	v_exp_f32_e32 v68, v68
	v_add_f32_e32 v97, 0, v64
	v_exp_f32_e32 v69, v69
	v_add_f32_e32 v97, v65, v97
	v_exp_f32_e32 v70, v70
	v_add_f32_e32 v97, v66, v97
	v_exp_f32_e32 v71, v71
	v_add_f32_e32 v97, v67, v97
	v_exp_f32_e32 v72, v72
	v_add_f32_e32 v97, v68, v97
	v_exp_f32_e32 v73, v73
	v_add_f32_e32 v97, v69, v97
	v_exp_f32_e32 v74, v74
	v_add_f32_e32 v97, v70, v97
	v_exp_f32_e32 v75, v75
	v_add_f32_e32 v97, v71, v97
	v_exp_f32_e32 v76, v76
	v_add_f32_e32 v97, v72, v97
	v_exp_f32_e32 v77, v77
	v_add_f32_e32 v97, v73, v97
	v_exp_f32_e32 v78, v78
	v_add_f32_e32 v97, v74, v97
	v_exp_f32_e32 v79, v79
	v_add_f32_e32 v97, v75, v97
	v_add_f32_e32 v97, v76, v97
	v_add_f32_e32 v97, v77, v97
	v_add_f32_e32 v97, v78, v97
	v_add_f32_e32 v97, v79, v97
	v_add_f32_e32 v96, v96, v97
	v_cvt_pk_bf16_f32 v64, v64, v65
	v_cvt_pk_bf16_f32 v65, v66, v67
	v_cvt_pk_bf16_f32 v66, v68, v69
	v_cvt_pk_bf16_f32 v67, v70, v71
	v_cvt_pk_bf16_f32 v68, v72, v73
	v_cvt_pk_bf16_f32 v69, v74, v75
	v_cvt_pk_bf16_f32 v70, v76, v77
	v_cvt_pk_bf16_f32 v71, v78, v79
	s_nop 0
	v_permlane32_swap_b32_e32 v64, v66
	v_permlane32_swap_b32_e32 v65, v67
	v_permlane32_swap_b32_e32 v68, v70
	v_permlane32_swap_b32_e32 v69, v71
	s_waitcnt lgkmcnt(0)
	s_setprio 1
	v_mfma_f32_32x32x16_bf16 v[0:15], v[64:67], v[132:135], v[0:15]
	s_cmp_lt_i32 s47, 64
	s_cselect_b64 s[0:1], -1, 0
	s_cmp_gt_i32 s45, 63
	s_cselect_b64 s[2:3], -1, 0
	s_and_b64 s[0:1], s[2:3], s[0:1]
	v_cndmask_b32_e64 v97, 0, 1, s[0:1]
	v_cmp_ne_u32_e64 s[2:3], 1, v97
	v_mfma_f32_32x32x16_bf16 v[48:63], v[64:67], v[140:143], v[48:63]
	v_sub_u32_e32 v97, 0xfc0, v111
	s_andn2_b64 vcc, exec, s[0:1]
	v_lshlrev_b32_e32 v97, 2, v97
	v_mfma_f32_32x32x16_bf16 v[16:31], v[64:67], v[148:151], v[16:31]
	v_mfma_f32_32x32x16_bf16 v[32:47], v[64:67], v[156:159], v[32:47]
	v_mfma_f32_32x32x16_bf16 v[0:15], v[68:71], v[136:139], v[0:15]
	v_mfma_f32_32x32x16_bf16 v[48:63], v[68:71], v[144:147], v[48:63]
	v_mfma_f32_32x32x16_bf16 v[16:31], v[68:71], v[152:155], v[16:31]
	v_mfma_f32_32x32x16_bf16 v[32:47], v[68:71], v[162:165], v[32:47]
	s_cmp_lt_u32 s33, 0x100
	s_cbranch_scc1 .Lstg_d1_m62_23
	s_waitcnt vmcnt(0)
	s_barrier

; #define LAS __attribute__((address_space(3)))
; DI void expsum(f32x16& p, float& l_reg, bf16x8& pa0, bf16x8& pa1) {
; #pragma unroll
;     for (int r = 0; r < 16; ++r) p[r] = __builtin_amdgcn_exp2f(p[r]);
;     float ps = 0.f;
; #pragma unroll
;     for (int r = 0; r < 16; ++r) ps += p[r];
;     l_reg += ps; asm volatile("" : "+v"(l_reg));
;     ...
;     ATT_PK4(p, 0, pa0); ATT_PK4(p, 8, pa1);
;     ...
; }
; DI int v_rd_base(int lane) { return ((lane & 3) << 3) | (((lane >> 2) & 3) << 6) | (((lane >> 4) & 1) << 5) | (((lane >> 5) & 1) << 8); }
; template <int OFF> DI s16x4 tr_read(int vb) { s16x4 r; asm volatile("ds_read_b64_tr_b16 %0, %1 offset:%2" : "=&v"(r) : "v"(vb), "i"(OFF) : "memory"); return r; }
; template <int H> DI void v_reads(s16x4* vf, int vb) {
;     vf[0] = tr_read<v_rd_off(0, 2 * H, 0)>(vb); vf[1] = tr_read<v_rd_off(0, 2 * H, 1)>(vb); vf[2] = tr_read<v_rd_off(0, 2 * H + 1, 0)>(vb); vf[3] = tr_read<v_rd_off(0, 2 * H + 1, 1)>(vb);
;     vf[4] = tr_read<v_rd_off(1, 2 * H, 0)>(vb); vf[5] = tr_read<v_rd_off(1, 2 * H, 1)>(vb); vf[6] = tr_read<v_rd_off(1, 2 * H + 1, 0)>(vb); vf[7] = tr_read<v_rd_off(1, 2 * H + 1, 1)>(vb);
;     vf[8] = tr_read<v_rd_off(2, 2 * H, 0)>(vb); vf[9] = tr_read<v_rd_off(2, 2 * H, 1)>(vb); vf[10] = tr_read<v_rd_off(2, 2 * H + 1, 0)>(vb); vf[11] = tr_read<v_rd_off(2, 2 * H + 1, 1)>(vb);
;     vf[12] = tr_read<v_rd_off(3, 2 * H, 0)>(vb); vf[13] = tr_read<v_rd_off(3, 2 * H, 1)>(vb); vf[14] = tr_read<v_rd_off(3, 2 * H + 1, 0)>(vb); vf[15] = tr_read<v_rd_off(3, 2 * H + 1, 1)>(vb);
; }
; DI void pv_mma(f32x16* o, const s16x4* vf, bf16x8 pa0, bf16x8 pa1) {
;     ...
; #pragma unroll
;     for (int d0 = 0; d0 < 4; ++d0) {
;         o[d0] = __builtin_amdgcn_mfma_f32_32x32x16_bf16(pa0, ATT_PK(vf[4 * d0], vf[4 * d0 + 1]), o[d0], 0, 0, 0);
;         o[d0] = __builtin_amdgcn_mfma_f32_32x32x16_bf16(pa1, ATT_PK(vf[4 * d0 + 2], vf[4 * d0 + 3]), o[d0], 0, 0, 0); }
;     ...
; }
; template <int DQK, int D0A, int D0B> DI void k_reads(bf16x8* kf, const LAS unsigned char* Ks, int half, int r32, int hi) {
; #pragma unroll
;     for (int d0 = D0A; d0 < D0B; ++d0) kf[d0 - D0A] = *(const LAS bf16x8*)(Ks + half * (32 * DQK * 2) + kswz<DQK>(r32, (d0 * 16 + hi * 8) * 2));
; }
; template <int D0A, int D0B> DI void qk_mma(f32x16& p, const bf16x8* kf, const bf16x8* qr) {
; #pragma unroll
;     for (int d0 = D0A; d0 < D0B; ++d0) {
.Lstg_mla_top_2:
	s_setprio 0
	s_mov_b32 m0, s1
	s_mov_b32 s0, s5
	s_mov_b32 s5, s44
	s_mov_b32 s44, s4
	s_lshl_b32 s4, s4, 14
	global_load_lds_dwordx4 v136, s[34:35]
	s_add_i32 m0, s1, 0x2000
	s_add_i32 s4, s52, s4
	global_load_lds_dwordx4 v138, s[34:35]
	s_add_i32 m0, s1, 0x4000
	s_add_i32 s6, s4, 0x400
	global_load_lds_dwordx4 v140, s[34:35]
	s_mov_b32 m0, s4
	s_add_i32 s1, s43, -3
	global_load_lds_dwordx4 v144, s[34:35]
	s_mov_b32 m0, s6
	s_nop 0
	global_load_lds_dwordx4 v142, s[34:35]
	s_and_b32 s1, s1, 3
	s_mulk_i32 s1, 0x6000
	v_add_u32_e32 v246, s1, v158
	v_add_u32_e32 v174, v246, v151
	v_add_u32_e32 v178, v246, v149
	v_add_u32_e32 v182, v246, v148
	v_add_u32_e32 v186, v246, v147
	v_add_u32_e32 v190, v246, v146
	v_add_u32_e32 v194, v246, v150
	s_lshl_b32 s1, s0, 14
	ds_read_b128 v[174:177], v174 offset:12288
	ds_read_b128 v[178:181], v178 offset:12288
	ds_read_b128 v[182:185], v182 offset:12288
	ds_read_b128 v[186:189], v186 offset:12288
	ds_read_b128 v[190:193], v190 offset:12288
	ds_read_b128 v[194:197], v194 offset:12288
	v_add_u32_e32 v254, s1, v130
	ds_read_b64_tr_b16 v[198:199], v254 offset:0
	ds_read_b64_tr_b16 v[200:201], v254 offset:0x800
	ds_read_b64_tr_b16 v[202:203], v254 offset:0x1000
	ds_read_b64_tr_b16 v[204:205], v254 offset:0x1800
	ds_read_b64_tr_b16 v[206:207], v254 offset:0x200
	ds_read_b64_tr_b16 v[208:209], v254 offset:0xa00
	ds_read_b64_tr_b16 v[210:211], v254 offset:0x1200
	ds_read_b64_tr_b16 v[212:213], v254 offset:0x1a00
	ds_read_b64_tr_b16 v[214:215], v254 offset:0x400
	ds_read_b64_tr_b16 v[216:217], v254 offset:0xc00
	ds_read_b64_tr_b16 v[218:219], v254 offset:0x1400
	ds_read_b64_tr_b16 v[220:221], v254 offset:0x1c00
	ds_read_b64_tr_b16 v[222:223], v254 offset:0x600
	ds_read_b64_tr_b16 v[224:225], v254 offset:0xe00
	ds_read_b64_tr_b16 v[226:227], v254 offset:0x1600
	ds_read_b64_tr_b16 v[228:229], v254 offset:0x1e00
	s_setprio 2
	v_exp_f32_e32 v64, v64
	v_exp_f32_e32 v65, v65
	v_exp_f32_e32 v66, v66
	v_exp_f32_e32 v67, v67
	v_exp_f32_e32 v68, v68
	v_add_f32_e32 v230, 0, v64
	v_exp_f32_e32 v69, v69
	v_add_f32_e32 v230, v65, v230
	v_exp_f32_e32 v70, v70
	v_add_f32_e32 v230, v66, v230
	v_exp_f32_e32 v71, v71
	v_add_f32_e32 v230, v67, v230
	v_exp_f32_e32 v72, v72
	v_add_f32_e32 v230, v68, v230
	v_exp_f32_e32 v73, v73
	v_add_f32_e32 v230, v69, v230
	v_exp_f32_e32 v74, v74
	v_add_f32_e32 v230, v70, v230
	v_exp_f32_e32 v75, v75
	v_add_f32_e32 v230, v71, v230
	v_exp_f32_e32 v76, v76
	v_add_f32_e32 v230, v72, v230
	v_exp_f32_e32 v77, v77
	v_add_f32_e32 v230, v73, v230
	v_exp_f32_e32 v78, v78
	v_add_f32_e32 v230, v74, v230
	v_exp_f32_e32 v79, v79
	v_add_f32_e32 v230, v75, v230
	v_add_f32_e32 v230, v76, v230
	v_add_f32_e32 v230, v77, v230
	v_add_f32_e32 v230, v78, v230
	v_add_f32_e32 v230, v79, v230
	v_add_f32_e32 v173, v173, v230
	v_cvt_pk_bf16_f32 v64, v64, v65
	v_cvt_pk_bf16_f32 v65, v66, v67
	v_cvt_pk_bf16_f32 v66, v68, v69
	v_cvt_pk_bf16_f32 v67, v70, v71
	v_cvt_pk_bf16_f32 v68, v72, v73
	v_cvt_pk_bf16_f32 v69, v74, v75
	v_cvt_pk_bf16_f32 v70, v76, v77
	v_cvt_pk_bf16_f32 v71, v78, v79
	s_nop 0
	v_permlane32_swap_b32_e32 v64, v66
	v_permlane32_swap_b32_e32 v65, v67
	v_permlane32_swap_b32_e32 v68, v70
	v_permlane32_swap_b32_e32 v69, v71
	s_waitcnt lgkmcnt(0)
	v_add_u32_e32 v72, v246, v152
	v_add_u32_e32 v73, v246, v153
	ds_read_b128 v[230:233], v72 offset:12288
	ds_read_b128 v[234:237], v73 offset:12288
	v_add_u32_e32 v72, v246, v154
	v_add_u32_e32 v73, v246, v155
	ds_read_b128 v[238:241], v72 offset:12288
	ds_read_b128 v[242:245], v73 offset:12288
	v_add_u32_e32 v72, v246, v156
	v_add_u32_e32 v73, v246, v157
	ds_read_b128 v[246:249], v72 offset:12288
	ds_read_b128 v[250:253], v73 offset:12288
	s_setprio 1
	v_mfma_f32_32x32x16_bf16 v[48:63], v[64:67], v[198:201], v[48:63]
	v_mfma_f32_32x32x16_bf16 v[32:47], v[64:67], v[206:209], v[32:47]
	v_mfma_f32_32x32x16_bf16 v[16:31], v[64:67], v[214:217], v[16:31]
	v_mfma_f32_32x32x16_bf16 v[0:15], v[64:67], v[222:225], v[0:15]
	v_mfma_f32_32x32x16_bf16 v[48:63], v[68:71], v[202:205], v[48:63]
	v_mfma_f32_32x32x16_bf16 v[32:47], v[68:71], v[210:213], v[32:47]
	v_mfma_f32_32x32x16_bf16 v[16:31], v[68:71], v[218:221], v[16:31]
	v_mfma_f32_32x32x16_bf16 v[0:15], v[68:71], v[226:229], v[0:15]
	s_waitcnt lgkmcnt(0)
; #define LAS __attribute__((address_space(3)))
; DI void expsum(f32x16& p, float& l_reg, bf16x8& pa0, bf16x8& pa1) {
; #pragma unroll
;     for (int r = 0; r < 16; ++r) p[r] = __builtin_amdgcn_exp2f(p[r]);
;     float ps = 0.f;
; #pragma unroll
;     for (int r = 0; r < 16; ++r) ps += p[r];
;     l_reg += ps; asm volatile("" : "+v"(l_reg));
;     ...
;     ATT_PK4(p, 0, pa0); ATT_PK4(p, 8, pa1);
;     ...
; }
; DI int v_rd_base(int lane) { return ((lane & 3) << 3) | (((lane >> 2) & 3) << 6) | (((lane >> 4) & 1) << 5) | (((lane >> 5) & 1) << 8); }
; template <int OFF> DI s16x4 tr_read(int vb) { s16x4 r; asm volatile("ds_read_b64_tr_b16 %0, %1 offset:%2" : "=&v"(r) : "v"(vb), "i"(OFF) : "memory"); return r; }
; template <int H> DI void v_reads(s16x4* vf, int vb) {
;     vf[0] = tr_read<v_rd_off(0, 2 * H, 0)>(vb); vf[1] = tr_read<v_rd_off(0, 2 * H, 1)>(vb); vf[2] = tr_read<v_rd_off(0, 2 * H + 1, 0)>(vb); vf[3] = tr_read<v_rd_off(0, 2 * H + 1, 1)>(vb);
;     vf[4] = tr_read<v_rd_off(1, 2 * H, 0)>(vb); vf[5] = tr_read<v_rd_off(1, 2 * H, 1)>(vb); vf[6] = tr_read<v_rd_off(1, 2 * H + 1, 0)>(vb); vf[7] = tr_read<v_rd_off(1, 2 * H + 1, 1)>(vb);
;     vf[8] = tr_read<v_rd_off(2, 2 * H, 0)>(vb); vf[9] = tr_read<v_rd_off(2, 2 * H, 1)>(vb); vf[10] = tr_read<v_rd_off(2, 2 * H + 1, 0)>(vb); vf[11] = tr_read<v_rd_off(2, 2 * H + 1, 1)>(vb);
;     vf[12] = tr_read<v_rd_off(3, 2 * H, 0)>(vb); vf[13] = tr_read<v_rd_off(3, 2 * H, 1)>(vb); vf[14] = tr_read<v_rd_off(3, 2 * H + 1, 0)>(vb); vf[15] = tr_read<v_rd_off(3, 2 * H + 1, 1)>(vb);
; }
; DI void pv_mma(f32x16* o, const s16x4* vf, bf16x8 pa0, bf16x8 pa1) {
;     ...
; #pragma unroll
;     for (int d0 = 0; d0 < 4; ++d0) {
;         o[d0] = __builtin_amdgcn_mfma_f32_32x32x16_bf16(pa0, ATT_PK(vf[4 * d0], vf[4 * d0 + 1]), o[d0], 0, 0, 0);
;         o[d0] = __builtin_amdgcn_mfma_f32_32x32x16_bf16(pa1, ATT_PK(vf[4 * d0 + 2], vf[4 * d0 + 3]), o[d0], 0, 0, 0); }
;     ...
; }
; template <int DQK, int D0A, int D0B> DI void k_reads(bf16x8* kf, const LAS unsigned char* Ks, int half, int r32, int hi) {
; #pragma unroll
;     for (int d0 = D0A; d0 < D0B; ++d0) kf[d0 - D0A] = *(const LAS bf16x8*)(Ks + half * (32 * DQK * 2) + kswz<DQK>(r32, (d0 * 16 + hi * 8) * 2));
; }
; template <int D0A, int D0B> DI void qk_mma(f32x16& p, const bf16x8* kf, const bf16x8* qr) {
; #pragma unroll
;     for (int d0 = D0A; d0 < D0B; ++d0) {
	v_mfma_f32_32x32x16_bf16 v[64:79], v[174:177], v[80:83], 0
	v_mfma_f32_32x32x16_bf16 v[64:79], v[178:181], v[84:87], v[64:79]
	v_mfma_f32_32x32x16_bf16 v[64:79], v[182:185], v[88:91], v[64:79]
	v_mfma_f32_32x32x16_bf16 v[64:79], v[186:189], v[92:95], v[64:79]
	v_mfma_f32_32x32x16_bf16 v[64:79], v[190:193], v[96:99], v[64:79]
	v_mfma_f32_32x32x16_bf16 v[64:79], v[194:197], v[100:103], v[64:79]
	v_mfma_f32_32x32x16_bf16 v[64:79], v[230:233], v[104:107], v[64:79]
	v_mfma_f32_32x32x16_bf16 v[64:79], v[234:237], v[108:111], v[64:79]
	v_mfma_f32_32x32x16_bf16 v[64:79], v[238:241], v[112:115], v[64:79]
	v_mfma_f32_32x32x16_bf16 v[64:79], v[242:245], v[116:119], v[64:79]
	v_mfma_f32_32x32x16_bf16 v[64:79], v[246:249], v[120:123], v[64:79]
	v_mfma_f32_32x32x16_bf16 v[64:79], v[250:253], v[124:127], v[64:79]
	s_setprio 0
	s_add_i32 s4, s43, -2
	s_and_b32 s4, s4, 3
	s_mulk_i32 s4, 0x6000
	v_add_u32_e32 v246, s4, v158
	v_add_u32_e32 v174, v246, v151
	v_add_u32_e32 v178, v246, v149
	v_add_u32_e32 v182, v246, v148
	v_add_u32_e32 v186, v246, v147
	v_add_u32_e32 v190, v246, v146
	v_add_u32_e32 v194, v246, v150
	ds_read_b128 v[174:177], v174
	ds_read_b128 v[178:181], v178
	ds_read_b128 v[182:185], v182
	ds_read_b128 v[186:189], v186
	ds_read_b128 v[190:193], v190
	ds_read_b128 v[194:197], v194
	ds_read_b64_tr_b16 v[198:199], v254 offset:0x2000
	ds_read_b64_tr_b16 v[200:201], v254 offset:0x2800
	ds_read_b64_tr_b16 v[202:203], v254 offset:0x3000
	ds_read_b64_tr_b16 v[204:205], v254 offset:0x3800
	ds_read_b64_tr_b16 v[206:207], v254 offset:0x2200
	ds_read_b64_tr_b16 v[208:209], v254 offset:0x2a00
	ds_read_b64_tr_b16 v[210:211], v254 offset:0x3200
	ds_read_b64_tr_b16 v[212:213], v254 offset:0x3a00
	ds_read_b64_tr_b16 v[214:215], v254 offset:0x2400
	ds_read_b64_tr_b16 v[216:217], v254 offset:0x2c00
	ds_read_b64_tr_b16 v[218:219], v254 offset:0x3400
	ds_read_b64_tr_b16 v[220:221], v254 offset:0x3c00
	ds_read_b64_tr_b16 v[222:223], v254 offset:0x2600
	ds_read_b64_tr_b16 v[224:225], v254 offset:0x2e00
	ds_read_b64_tr_b16 v[226:227], v254 offset:0x3600
	ds_read_b64_tr_b16 v[228:229], v254 offset:0x3e00
	s_setprio 2
	v_exp_f32_e32 v64, v64
	v_exp_f32_e32 v65, v65
	v_exp_f32_e32 v66, v66
	v_exp_f32_e32 v67, v67
	v_exp_f32_e32 v68, v68
	v_add_f32_e32 v230, 0, v64
	v_exp_f32_e32 v69, v69
	v_add_f32_e32 v230, v65, v230
	v_exp_f32_e32 v70, v70
	v_add_f32_e32 v230, v66, v230
	v_exp_f32_e32 v71, v71
	v_add_f32_e32 v230, v67, v230
	v_exp_f32_e32 v72, v72
	v_add_f32_e32 v230, v68, v230
	v_exp_f32_e32 v73, v73
	v_add_f32_e32 v230, v69, v230
	v_exp_f32_e32 v74, v74
	v_add_f32_e32 v230, v70, v230
	v_exp_f32_e32 v75, v75
	v_add_f32_e32 v230, v71, v230
	v_exp_f32_e32 v76, v76
	v_add_f32_e32 v230, v72, v230
	v_exp_f32_e32 v77, v77
	v_add_f32_e32 v230, v73, v230
	v_exp_f32_e32 v78, v78
	v_add_f32_e32 v230, v74, v230
	v_exp_f32_e32 v79, v79
	v_add_f32_e32 v230, v75, v230
	v_add_f32_e32 v230, v76, v230
	v_add_f32_e32 v230, v77, v230
	v_add_f32_e32 v230, v78, v230
	v_add_f32_e32 v230, v79, v230
	v_add_f32_e32 v173, v173, v230
	v_cvt_pk_bf16_f32 v64, v64, v65
	v_cvt_pk_bf16_f32 v65, v66, v67
	v_cvt_pk_bf16_f32 v66, v68, v69
	v_cvt_pk_bf16_f32 v67, v70, v71
	v_cvt_pk_bf16_f32 v68, v72, v73
	v_cvt_pk_bf16_f32 v69, v74, v75
	v_cvt_pk_bf16_f32 v70, v76, v77
	v_cvt_pk_bf16_f32 v71, v78, v79
	s_nop 0
	v_permlane32_swap_b32_e32 v64, v66
	v_permlane32_swap_b32_e32 v65, v67
	v_permlane32_swap_b32_e32 v68, v70
	v_permlane32_swap_b32_e32 v69, v71
	s_waitcnt lgkmcnt(0)
	v_add_u32_e32 v72, v246, v152
	v_add_u32_e32 v73, v246, v153
	ds_read_b128 v[230:233], v72
	ds_read_b128 v[234:237], v73
	v_add_u32_e32 v72, v246, v154
	v_add_u32_e32 v73, v246, v155
	ds_read_b128 v[238:241], v72
	ds_read_b128 v[242:245], v73
	v_add_u32_e32 v72, v246, v156
	v_add_u32_e32 v73, v246, v157
	ds_read_b128 v[246:249], v72
	ds_read_b128 v[250:253], v73
	s_setprio 1
	v_mfma_f32_32x32x16_bf16 v[48:63], v[64:67], v[198:201], v[48:63]
	v_mfma_f32_32x32x16_bf16 v[32:47], v[64:67], v[206:209], v[32:47]
	v_mfma_f32_32x32x16_bf16 v[16:31], v[64:67], v[214:217], v[16:31]
	v_mfma_f32_32x32x16_bf16 v[0:15], v[64:67], v[222:225], v[0:15]
	v_mfma_f32_32x32x16_bf16 v[48:63], v[68:71], v[202:205], v[48:63]
	v_mfma_f32_32x32x16_bf16 v[32:47], v[68:71], v[210:213], v[32:47]
	v_mfma_f32_32x32x16_bf16 v[16:31], v[68:71], v[218:221], v[16:31]
	v_mfma_f32_32x32x16_bf16 v[0:15], v[68:71], v[226:229], v[0:15]
	s_cmp_lt_u32 s33, 0x100
	s_cbranch_scc1 .Lstg_mla_mid_3
	s_waitcnt vmcnt(5)
	s_barrier
.Lstg_mla_mid_3:
	s_waitcnt lgkmcnt(0)
	v_mfma_f32_32x32x16_bf16 v[64:79], v[174:177], v[80:83], 0
	v_mfma_f32_32x32x16_bf16 v[64:79], v[178:181], v[84:87], v[64:79]
	v_mfma_f32_32x32x16_bf16 v[64:79], v[182:185], v[88:91], v[64:79]
	v_mfma_f32_32x32x16_bf16 v[64:79], v[186:189], v[92:95], v[64:79]
	v_mfma_f32_32x32x16_bf16 v[64:79], v[190:193], v[96:99], v[64:79]
	v_mfma_f32_32x32x16_bf16 v[64:79], v[194:197], v[100:103], v[64:79]
	v_mfma_f32_32x32x16_bf16 v[64:79], v[230:233], v[104:107], v[64:79]
	v_mfma_f32_32x32x16_bf16 v[64:79], v[234:237], v[108:111], v[64:79]
	v_mfma_f32_32x32x16_bf16 v[64:79], v[238:241], v[112:115], v[64:79]
	v_mfma_f32_32x32x16_bf16 v[64:79], v[242:245], v[116:119], v[64:79]
	v_mfma_f32_32x32x16_bf16 v[64:79], v[246:249], v[120:123], v[64:79]
	v_mfma_f32_32x32x16_bf16 v[64:79], v[250:253], v[124:127], v[64:79]
	s_add_i32 s43, s43, 1
	v_add_u32_e32 v136, s36, v136
	v_add_u32_e32 v138, s36, v138
	v_add_u32_e32 v140, s36, v140
	v_add_u32_e32 v142, s38, v142
	v_add_u32_e32 v144, s38, v144
	s_cmp_eq_u32 s43, 64
	s_mov_b32 s4, s0
	s_cbranch_scc0 .LBB0_1982
	s_lshl_b32 s0, s55, 2
	s_add_i32 s4, s0, 0
	s_add_i32 s6, s52, s1
	s_add_i32 s4, s4, 0x24000
	s_add_i32 s7, s6, 0x400
	s_add_u32 s0, s2, 0x3f0000
	s_addc_u32 s1, s3, 0
	s_cmp_lt_u32 s33, 0x100
	s_cbranch_scc0 .Lstg_mla_t61_4
	s_waitcnt vmcnt(5)
	s_barrier
; #define LAS __attribute__((address_space(3)))
; DI void expsum(f32x16& p, float& l_reg, bf16x8& pa0, bf16x8& pa1) {
; #pragma unroll
;     for (int r = 0; r < 16; ++r) p[r] = __builtin_amdgcn_exp2f(p[r]);
;     float ps = 0.f;
; #pragma unroll
;     for (int r = 0; r < 16; ++r) ps += p[r];
;     l_reg += ps; asm volatile("" : "+v"(l_reg));
;     ...
;     ATT_PK4(p, 0, pa0); ATT_PK4(p, 8, pa1);
;     ...
; }
; DI int v_rd_base(int lane) { return ((lane & 3) << 3) | (((lane >> 2) & 3) << 6) | (((lane >> 4) & 1) << 5) | (((lane >> 5) & 1) << 8); }
; template <int OFF> DI s16x4 tr_read(int vb) { s16x4 r; asm volatile("ds_read_b64_tr_b16 %0, %1 offset:%2" : "=&v"(r) : "v"(vb), "i"(OFF) : "memory"); return r; }
; template <int H> DI void v_reads(s16x4* vf, int vb) {
;     vf[0] = tr_read<v_rd_off(0, 2 * H, 0)>(vb); vf[1] = tr_read<v_rd_off(0, 2 * H, 1)>(vb); vf[2] = tr_read<v_rd_off(0, 2 * H + 1, 0)>(vb); vf[3] = tr_read<v_rd_off(0, 2 * H + 1, 1)>(vb);
;     vf[4] = tr_read<v_rd_off(1, 2 * H, 0)>(vb); vf[5] = tr_read<v_rd_off(1, 2 * H, 1)>(vb); vf[6] = tr_read<v_rd_off(1, 2 * H + 1, 0)>(vb); vf[7] = tr_read<v_rd_off(1, 2 * H + 1, 1)>(vb);
;     vf[8] = tr_read<v_rd_off(2, 2 * H, 0)>(vb); vf[9] = tr_read<v_rd_off(2, 2 * H, 1)>(vb); vf[10] = tr_read<v_rd_off(2, 2 * H + 1, 0)>(vb); vf[11] = tr_read<v_rd_off(2, 2 * H + 1, 1)>(vb);
;     vf[12] = tr_read<v_rd_off(3, 2 * H, 0)>(vb); vf[13] = tr_read<v_rd_off(3, 2 * H, 1)>(vb); vf[14] = tr_read<v_rd_off(3, 2 * H + 1, 0)>(vb); vf[15] = tr_read<v_rd_off(3, 2 * H + 1, 1)>(vb);
; }
; DI void pv_mma(f32x16* o, const s16x4* vf, bf16x8 pa0, bf16x8 pa1) {
;     ...
; #pragma unroll
;     for (int d0 = 0; d0 < 4; ++d0) {
;         o[d0] = __builtin_amdgcn_mfma_f32_32x32x16_bf16(pa0, ATT_PK(vf[4 * d0], vf[4 * d0 + 1]), o[d0], 0, 0, 0);
;         o[d0] = __builtin_amdgcn_mfma_f32_32x32x16_bf16(pa1, ATT_PK(vf[4 * d0 + 2], vf[4 * d0 + 3]), o[d0], 0, 0, 0); }
;     ...
; }
; template <int DQK, int D0A, int D0B> DI void k_reads(bf16x8* kf, const LAS unsigned char* Ks, int half, int r32, int hi) {
; #pragma unroll
;     for (int d0 = D0A; d0 < D0B; ++d0) kf[d0 - D0A] = *(const LAS bf16x8*)(Ks + half * (32 * DQK * 2) + kswz<DQK>(r32, (d0 * 16 + hi * 8) * 2));
; }
; template <int D0A, int D0B> DI void qk_mma(f32x16& p, const bf16x8* kf, const bf16x8* qr) {
; #pragma unroll
;     for (int d0 = D0A; d0 < D0B; ++d0) {
.Lstg_mla_t61_4:
	s_setprio 0
	v_lshl_add_u64 v[132:133], v[132:133], 1, s[0:1]
	s_mov_b32 m0, s6
	v_lshl_add_u64 v[134:135], v[134:135], 1, s[0:1]
	global_load_lds_dwordx4 v[132:133], off
	s_mov_b32 m0, s7
	s_nop 0
	global_load_lds_dwordx4 v[134:135], off
	ds_read_b128 v[132:135], v161 offset:36864
	ds_read_b128 v[136:139], v162 offset:36864
	ds_read_b128 v[140:143], v163 offset:36864
	ds_read_b128 v[174:177], v164 offset:36864
	ds_read_b128 v[178:181], v165 offset:36864
	ds_read_b128 v[182:185], v166 offset:36864
	v_lshl_add_u32 v144, s5, 14, v130
	ds_read_b64_tr_b16 v[186:187], v144 offset:0
	ds_read_b64_tr_b16 v[188:189], v144 offset:0x800
	ds_read_b64_tr_b16 v[190:191], v144 offset:0x1000
	ds_read_b64_tr_b16 v[192:193], v144 offset:0x1800
	ds_read_b64_tr_b16 v[194:195], v144 offset:0x200
	ds_read_b64_tr_b16 v[196:197], v144 offset:0xa00
	ds_read_b64_tr_b16 v[198:199], v144 offset:0x1200
	ds_read_b64_tr_b16 v[200:201], v144 offset:0x1a00
	ds_read_b64_tr_b16 v[202:203], v144 offset:0x400
	ds_read_b64_tr_b16 v[204:205], v144 offset:0xc00
	ds_read_b64_tr_b16 v[206:207], v144 offset:0x1400
	ds_read_b64_tr_b16 v[208:209], v144 offset:0x1c00
	ds_read_b64_tr_b16 v[210:211], v144 offset:0x600
	ds_read_b64_tr_b16 v[212:213], v144 offset:0xe00
	ds_read_b64_tr_b16 v[214:215], v144 offset:0x1600
	ds_read_b64_tr_b16 v[216:217], v144 offset:0x1e00
	s_setprio 2
	v_exp_f32_e32 v64, v64
	v_exp_f32_e32 v65, v65
	v_exp_f32_e32 v66, v66
	v_exp_f32_e32 v67, v67
	v_exp_f32_e32 v68, v68
	v_add_f32_e32 v145, 0, v64
	v_exp_f32_e32 v69, v69
	v_add_f32_e32 v145, v65, v145
	v_exp_f32_e32 v70, v70
	v_add_f32_e32 v145, v66, v145
	v_exp_f32_e32 v71, v71
	v_add_f32_e32 v145, v67, v145
	v_exp_f32_e32 v72, v72
	v_add_f32_e32 v145, v68, v145
	v_exp_f32_e32 v73, v73
	v_add_f32_e32 v145, v69, v145
	v_exp_f32_e32 v74, v74
	v_add_f32_e32 v145, v70, v145
	v_exp_f32_e32 v75, v75
	v_add_f32_e32 v145, v71, v145
	v_exp_f32_e32 v76, v76
	v_add_f32_e32 v145, v72, v145
	v_exp_f32_e32 v77, v77
	v_add_f32_e32 v145, v73, v145
	v_exp_f32_e32 v78, v78
	v_add_f32_e32 v145, v74, v145
	v_exp_f32_e32 v79, v79
	v_add_f32_e32 v145, v75, v145
	v_add_f32_e32 v145, v76, v145
	v_add_f32_e32 v145, v77, v145
	v_add_f32_e32 v145, v78, v145
	v_add_f32_e32 v145, v79, v145
	v_add_f32_e32 v145, v173, v145
	v_cvt_pk_bf16_f32 v64, v64, v65
	v_cvt_pk_bf16_f32 v65, v66, v67
	v_cvt_pk_bf16_f32 v66, v68, v69
	v_cvt_pk_bf16_f32 v67, v70, v71
	v_cvt_pk_bf16_f32 v68, v72, v73
	v_cvt_pk_bf16_f32 v69, v74, v75
	v_cvt_pk_bf16_f32 v70, v76, v77
	v_cvt_pk_bf16_f32 v71, v78, v79
	s_nop 0
	v_permlane32_swap_b32_e32 v64, v66
	v_permlane32_swap_b32_e32 v65, v67
	v_permlane32_swap_b32_e32 v68, v70
	v_permlane32_swap_b32_e32 v69, v71
	s_waitcnt lgkmcnt(0)
	ds_read_b128 v[218:221], v167 offset:36864
	ds_read_b128 v[222:225], v168 offset:36864
	ds_read_b128 v[226:229], v169 offset:36864
	ds_read_b128 v[230:233], v170 offset:36864
	ds_read_b128 v[234:237], v171 offset:36864
	ds_read_b128 v[238:241], v172 offset:36864
	s_setprio 1
	v_mfma_f32_32x32x16_bf16 v[48:63], v[64:67], v[186:189], v[48:63]
	v_mfma_f32_32x32x16_bf16 v[32:47], v[64:67], v[194:197], v[32:47]
	v_mfma_f32_32x32x16_bf16 v[16:31], v[64:67], v[202:205], v[16:31]
	v_mfma_f32_32x32x16_bf16 v[0:15], v[64:67], v[210:213], v[0:15]
	v_mfma_f32_32x32x16_bf16 v[48:63], v[68:71], v[190:193], v[48:63]
	v_mfma_f32_32x32x16_bf16 v[32:47], v[68:71], v[198:201], v[32:47]
	v_mfma_f32_32x32x16_bf16 v[16:31], v[68:71], v[206:209], v[16:31]
	v_mfma_f32_32x32x16_bf16 v[0:15], v[68:71], v[214:217], v[0:15]
	s_waitcnt lgkmcnt(0)
	v_mfma_f32_32x32x16_bf16 v[64:79], v[132:135], v[80:83], 0
	v_mfma_f32_32x32x16_bf16 v[64:79], v[136:139], v[84:87], v[64:79]
	v_mfma_f32_32x32x16_bf16 v[64:79], v[140:143], v[88:91], v[64:79]
	v_mfma_f32_32x32x16_bf16 v[64:79], v[174:177], v[92:95], v[64:79]
	v_mfma_f32_32x32x16_bf16 v[64:79], v[178:181], v[96:99], v[64:79]
	v_mfma_f32_32x32x16_bf16 v[64:79], v[182:185], v[100:103], v[64:79]
	s_waitcnt lgkmcnt(0)
	v_mfma_f32_32x32x16_bf16 v[64:79], v[218:221], v[104:107], v[64:79]
	v_mfma_f32_32x32x16_bf16 v[64:79], v[222:225], v[108:111], v[64:79]
	v_mfma_f32_32x32x16_bf16 v[64:79], v[226:229], v[112:115], v[64:79]
	v_mfma_f32_32x32x16_bf16 v[64:79], v[230:233], v[116:119], v[64:79]
	v_mfma_f32_32x32x16_bf16 v[64:79], v[234:237], v[120:123], v[64:79]
	v_mfma_f32_32x32x16_bf16 v[64:79], v[238:241], v[124:127], v[64:79]
	s_setprio 0
	ds_read_b128 v[132:135], v161 offset:49152
	ds_read_b128 v[136:139], v162 offset:49152
	ds_read_b128 v[140:143], v163 offset:49152
	ds_read_b128 v[174:177], v164 offset:49152
	ds_read_b128 v[178:181], v165 offset:49152
	ds_read_b128 v[182:185], v166 offset:49152
	ds_read_b64_tr_b16 v[186:187], v144 offset:0x2000
	ds_read_b64_tr_b16 v[188:189], v144 offset:0x2800
	ds_read_b64_tr_b16 v[190:191], v144 offset:0x3000
	ds_read_b64_tr_b16 v[192:193], v144 offset:0x3800
	ds_read_b64_tr_b16 v[194:195], v144 offset:0x2200
	ds_read_b64_tr_b16 v[196:197], v144 offset:0x2a00
	ds_read_b64_tr_b16 v[198:199], v144 offset:0x3200
	ds_read_b64_tr_b16 v[200:201], v144 offset:0x3a00
	ds_read_b64_tr_b16 v[202:203], v144 offset:0x2400
	ds_read_b64_tr_b16 v[204:205], v144 offset:0x2c00
	ds_read_b64_tr_b16 v[206:207], v144 offset:0x3400
	ds_read_b64_tr_b16 v[208:209], v144 offset:0x3c00
	ds_read_b64_tr_b16 v[210:211], v144 offset:0x2600
	ds_read_b64_tr_b16 v[212:213], v144 offset:0x2e00
	ds_read_b64_tr_b16 v[214:215], v144 offset:0x3600
	ds_read_b64_tr_b16 v[216:217], v144 offset:0x3e00
	s_nop 5
	s_setprio 2
	v_exp_f32_e32 v64, v64
	v_exp_f32_e32 v65, v65
	v_exp_f32_e32 v66, v66
	v_exp_f32_e32 v67, v67
	v_exp_f32_e32 v68, v68
	v_add_f32_e32 v144, 0, v64
	v_exp_f32_e32 v69, v69
	v_add_f32_e32 v144, v65, v144
	v_exp_f32_e32 v70, v70
	v_add_f32_e32 v144, v66, v144
	v_exp_f32_e32 v71, v71
	v_add_f32_e32 v144, v67, v144
	v_exp_f32_e32 v72, v72
	v_add_f32_e32 v144, v68, v144
	v_exp_f32_e32 v73, v73
	v_add_f32_e32 v144, v69, v144
	v_exp_f32_e32 v74, v74
	v_add_f32_e32 v144, v70, v144
	v_exp_f32_e32 v75, v75
	v_add_f32_e32 v144, v71, v144
	v_exp_f32_e32 v76, v76
	v_add_f32_e32 v144, v72, v144
	v_exp_f32_e32 v77, v77
	v_add_f32_e32 v144, v73, v144
	v_exp_f32_e32 v78, v78
	v_add_f32_e32 v144, v74, v144
	v_exp_f32_e32 v79, v79
	v_add_f32_e32 v144, v75, v144
	v_add_f32_e32 v144, v76, v144
	v_add_f32_e32 v144, v77, v144
	v_add_f32_e32 v144, v78, v144
	v_add_f32_e32 v144, v79, v144
	v_add_f32_e32 v144, v145, v144
	v_cvt_pk_bf16_f32 v64, v64, v65
	v_cvt_pk_bf16_f32 v65, v66, v67
	v_cvt_pk_bf16_f32 v66, v68, v69
	v_cvt_pk_bf16_f32 v67, v70, v71
	v_cvt_pk_bf16_f32 v68, v72, v73
	v_cvt_pk_bf16_f32 v69, v74, v75
	v_cvt_pk_bf16_f32 v70, v76, v77
	v_cvt_pk_bf16_f32 v71, v78, v79
	s_nop 0
	v_permlane32_swap_b32_e32 v64, v66
	v_permlane32_swap_b32_e32 v65, v67
	v_permlane32_swap_b32_e32 v68, v70
	v_permlane32_swap_b32_e32 v69, v71
	s_waitcnt lgkmcnt(0)
; #define LAS __attribute__((address_space(3)))
; DI void expsum(f32x16& p, float& l_reg, bf16x8& pa0, bf16x8& pa1) {
; #pragma unroll
;     for (int r = 0; r < 16; ++r) p[r] = __builtin_amdgcn_exp2f(p[r]);
;     float ps = 0.f;
; #pragma unroll
;     for (int r = 0; r < 16; ++r) ps += p[r];
;     l_reg += ps; asm volatile("" : "+v"(l_reg));
;     ...
;     ATT_PK4(p, 0, pa0); ATT_PK4(p, 8, pa1);
;     ...
; }
; DI int v_rd_base(int lane) { return ((lane & 3) << 3) | (((lane >> 2) & 3) << 6) | (((lane >> 4) & 1) << 5) | (((lane >> 5) & 1) << 8); }
; template <int OFF> DI s16x4 tr_read(int vb) { s16x4 r; asm volatile("ds_read_b64_tr_b16 %0, %1 offset:%2" : "=&v"(r) : "v"(vb), "i"(OFF) : "memory"); return r; }
; template <int H> DI void v_reads(s16x4* vf, int vb) {
;     vf[0] = tr_read<v_rd_off(0, 2 * H, 0)>(vb); vf[1] = tr_read<v_rd_off(0, 2 * H, 1)>(vb); vf[2] = tr_read<v_rd_off(0, 2 * H + 1, 0)>(vb); vf[3] = tr_read<v_rd_off(0, 2 * H + 1, 1)>(vb);
;     vf[4] = tr_read<v_rd_off(1, 2 * H, 0)>(vb); vf[5] = tr_read<v_rd_off(1, 2 * H, 1)>(vb); vf[6] = tr_read<v_rd_off(1, 2 * H + 1, 0)>(vb); vf[7] = tr_read<v_rd_off(1, 2 * H + 1, 1)>(vb);
;     vf[8] = tr_read<v_rd_off(2, 2 * H, 0)>(vb); vf[9] = tr_read<v_rd_off(2, 2 * H, 1)>(vb); vf[10] = tr_read<v_rd_off(2, 2 * H + 1, 0)>(vb); vf[11] = tr_read<v_rd_off(2, 2 * H + 1, 1)>(vb);
;     vf[12] = tr_read<v_rd_off(3, 2 * H, 0)>(vb); vf[13] = tr_read<v_rd_off(3, 2 * H, 1)>(vb); vf[14] = tr_read<v_rd_off(3, 2 * H + 1, 0)>(vb); vf[15] = tr_read<v_rd_off(3, 2 * H + 1, 1)>(vb);
; }
; DI void pv_mma(f32x16* o, const s16x4* vf, bf16x8 pa0, bf16x8 pa1) {
;     ...
; #pragma unroll
;     for (int d0 = 0; d0 < 4; ++d0) {
;         o[d0] = __builtin_amdgcn_mfma_f32_32x32x16_bf16(pa0, ATT_PK(vf[4 * d0], vf[4 * d0 + 1]), o[d0], 0, 0, 0);
;         o[d0] = __builtin_amdgcn_mfma_f32_32x32x16_bf16(pa1, ATT_PK(vf[4 * d0 + 2], vf[4 * d0 + 3]), o[d0], 0, 0, 0); }
;     ...
; }
; template <int DQK, int D0A, int D0B> DI void k_reads(bf16x8* kf, const LAS unsigned char* Ks, int half, int r32, int hi) {
; #pragma unroll
;     for (int d0 = D0A; d0 < D0B; ++d0) kf[d0 - D0A] = *(const LAS bf16x8*)(Ks + half * (32 * DQK * 2) + kswz<DQK>(r32, (d0 * 16 + hi * 8) * 2));
; }
; template <int D0A, int D0B> DI void qk_mma(f32x16& p, const bf16x8* kf, const bf16x8* qr) {
; #pragma unroll
;     for (int d0 = D0A; d0 < D0B; ++d0) {
	ds_read_b128 v[218:221], v167 offset:49152
	ds_read_b128 v[222:225], v168 offset:49152
	ds_read_b128 v[226:229], v169 offset:49152
	ds_read_b128 v[230:233], v170 offset:49152
	ds_read_b128 v[234:237], v171 offset:49152
	ds_read_b128 v[238:241], v172 offset:49152
	s_setprio 1
	v_mfma_f32_32x32x16_bf16 v[48:63], v[64:67], v[186:189], v[48:63]
	v_mfma_f32_32x32x16_bf16 v[32:47], v[64:67], v[194:197], v[32:47]
	v_mfma_f32_32x32x16_bf16 v[16:31], v[64:67], v[202:205], v[16:31]
	v_mfma_f32_32x32x16_bf16 v[0:15], v[64:67], v[210:213], v[0:15]
	v_mfma_f32_32x32x16_bf16 v[48:63], v[68:71], v[190:193], v[48:63]
	v_mfma_f32_32x32x16_bf16 v[32:47], v[68:71], v[198:201], v[32:47]
	v_mfma_f32_32x32x16_bf16 v[16:31], v[68:71], v[206:209], v[16:31]
	v_mfma_f32_32x32x16_bf16 v[0:15], v[68:71], v[214:217], v[0:15]
	s_cmp_lt_u32 s33, 0x100
	s_cbranch_scc1 .Lstg_mla_m61_5
	s_waitcnt vmcnt(0)
	s_barrier
.Lstg_mla_m61_5:
	s_waitcnt lgkmcnt(0)
	v_mfma_f32_32x32x16_bf16 v[64:79], v[132:135], v[80:83], 0
	v_mfma_f32_32x32x16_bf16 v[64:79], v[136:139], v[84:87], v[64:79]
	v_mfma_f32_32x32x16_bf16 v[64:79], v[140:143], v[88:91], v[64:79]
	v_mfma_f32_32x32x16_bf16 v[64:79], v[174:177], v[92:95], v[64:79]
	v_mfma_f32_32x32x16_bf16 v[64:79], v[178:181], v[96:99], v[64:79]
	v_mfma_f32_32x32x16_bf16 v[64:79], v[182:185], v[100:103], v[64:79]
	s_waitcnt lgkmcnt(0)
	v_mfma_f32_32x32x16_bf16 v[64:79], v[218:221], v[104:107], v[64:79]
	v_mfma_f32_32x32x16_bf16 v[64:79], v[222:225], v[108:111], v[64:79]
	v_mfma_f32_32x32x16_bf16 v[64:79], v[226:229], v[112:115], v[64:79]
	v_mfma_f32_32x32x16_bf16 v[64:79], v[230:233], v[116:119], v[64:79]
	v_mfma_f32_32x32x16_bf16 v[64:79], v[234:237], v[120:123], v[64:79]
	v_mfma_f32_32x32x16_bf16 v[64:79], v[238:241], v[124:127], v[64:79]
	s_cmp_lt_u32 s33, 0x100
	s_cbranch_scc0 .Lstg_mla_t62_6
	s_waitcnt vmcnt(0)
	s_barrier
.Lstg_mla_t62_6:
	s_setprio 0
	ds_read_b128 v[132:135], v161 offset:61440
	ds_read_b128 v[136:139], v162 offset:61440
	ds_read_b128 v[140:143], v163 offset:61440
	ds_read_b128 v[174:177], v164 offset:61440
	ds_read_b128 v[162:165], v165 offset:61440
	ds_read_b128 v[178:181], v166 offset:61440
	v_add_u32_e32 v145, 0x8000, v130
	ds_read_b64_tr_b16 v[182:183], v145 offset:0
	ds_read_b64_tr_b16 v[184:185], v145 offset:0x800
	ds_read_b64_tr_b16 v[186:187], v145 offset:0x1000
	ds_read_b64_tr_b16 v[188:189], v145 offset:0x1800
	ds_read_b64_tr_b16 v[190:191], v145 offset:0x200
	ds_read_b64_tr_b16 v[192:193], v145 offset:0xa00
	ds_read_b64_tr_b16 v[194:195], v145 offset:0x1200
	ds_read_b64_tr_b16 v[196:197], v145 offset:0x1a00
	ds_read_b64_tr_b16 v[198:199], v145 offset:0x400
	ds_read_b64_tr_b16 v[200:201], v145 offset:0xc00
	ds_read_b64_tr_b16 v[202:203], v145 offset:0x1400
	ds_read_b64_tr_b16 v[204:205], v145 offset:0x1c00
	ds_read_b64_tr_b16 v[206:207], v145 offset:0x600
	ds_read_b64_tr_b16 v[208:209], v145 offset:0xe00
	ds_read_b64_tr_b16 v[210:211], v145 offset:0x1600
	ds_read_b64_tr_b16 v[212:213], v145 offset:0x1e00
	s_nop 3
	s_setprio 2
	v_exp_f32_e32 v64, v64
	v_exp_f32_e32 v65, v65
	v_exp_f32_e32 v66, v66
	v_exp_f32_e32 v67, v67
	v_exp_f32_e32 v68, v68
	v_add_f32_e32 v161, 0, v64
	v_exp_f32_e32 v69, v69
	v_add_f32_e32 v161, v65, v161
	v_exp_f32_e32 v70, v70
	v_add_f32_e32 v161, v66, v161
	v_exp_f32_e32 v71, v71
	v_add_f32_e32 v161, v67, v161
	v_exp_f32_e32 v72, v72
	v_add_f32_e32 v161, v68, v161
	v_exp_f32_e32 v73, v73
	v_add_f32_e32 v161, v69, v161
	v_exp_f32_e32 v74, v74
	v_add_f32_e32 v161, v70, v161
	v_exp_f32_e32 v75, v75
	v_add_f32_e32 v161, v71, v161
	v_exp_f32_e32 v76, v76
	v_add_f32_e32 v161, v72, v161
	v_exp_f32_e32 v77, v77
	v_add_f32_e32 v161, v73, v161
	v_exp_f32_e32 v78, v78
	v_add_f32_e32 v161, v74, v161
	v_exp_f32_e32 v79, v79
	v_add_f32_e32 v161, v75, v161
	v_add_f32_e32 v161, v76, v161
	v_add_f32_e32 v161, v77, v161
	v_add_f32_e32 v161, v78, v161
	v_add_f32_e32 v161, v79, v161
	v_add_f32_e32 v144, v144, v161
	v_cvt_pk_bf16_f32 v64, v64, v65
	v_cvt_pk_bf16_f32 v65, v66, v67
	v_cvt_pk_bf16_f32 v66, v68, v69
	v_cvt_pk_bf16_f32 v67, v70, v71
	v_cvt_pk_bf16_f32 v68, v72, v73
	v_cvt_pk_bf16_f32 v69, v74, v75
	v_cvt_pk_bf16_f32 v70, v76, v77
	v_cvt_pk_bf16_f32 v71, v78, v79
	s_nop 0
	v_permlane32_swap_b32_e32 v64, v66
	v_permlane32_swap_b32_e32 v65, v67
	v_permlane32_swap_b32_e32 v68, v70
	v_permlane32_swap_b32_e32 v69, v71
	s_waitcnt lgkmcnt(0)
	ds_read_b128 v[214:217], v167 offset:61440
	ds_read_b128 v[218:221], v168 offset:61440
	ds_read_b128 v[166:169], v169 offset:61440
	ds_read_b128 v[222:225], v170 offset:61440
	ds_read_b128 v[226:229], v171 offset:61440
	ds_read_b128 v[170:173], v172 offset:61440
	s_setprio 1
	v_mfma_f32_32x32x16_bf16 v[48:63], v[64:67], v[182:185], v[48:63]
	v_mfma_f32_32x32x16_bf16 v[32:47], v[64:67], v[190:193], v[32:47]
	v_mfma_f32_32x32x16_bf16 v[16:31], v[64:67], v[198:201], v[16:31]
	v_mfma_f32_32x32x16_bf16 v[0:15], v[64:67], v[206:209], v[0:15]
	v_mfma_f32_32x32x16_bf16 v[48:63], v[68:71], v[186:189], v[48:63]
	v_mfma_f32_32x32x16_bf16 v[32:47], v[68:71], v[194:197], v[32:47]
	v_mfma_f32_32x32x16_bf16 v[16:31], v[68:71], v[202:205], v[16:31]
	v_mfma_f32_32x32x16_bf16 v[0:15], v[68:71], v[210:213], v[0:15]
	s_waitcnt lgkmcnt(0)
; #define LAS __attribute__((address_space(3)))
; DI void expsum(f32x16& p, float& l_reg, bf16x8& pa0, bf16x8& pa1) {
; #pragma unroll
;     for (int r = 0; r < 16; ++r) p[r] = __builtin_amdgcn_exp2f(p[r]);
;     float ps = 0.f;
; #pragma unroll
;     for (int r = 0; r < 16; ++r) ps += p[r];
;     l_reg += ps; asm volatile("" : "+v"(l_reg));
;     ...
;     ATT_PK4(p, 0, pa0); ATT_PK4(p, 8, pa1);
;     ...
; }
; DI int v_rd_base(int lane) { return ((lane & 3) << 3) | (((lane >> 2) & 3) << 6) | (((lane >> 4) & 1) << 5) | (((lane >> 5) & 1) << 8); }
; template <int OFF> DI s16x4 tr_read(int vb) { s16x4 r; asm volatile("ds_read_b64_tr_b16 %0, %1 offset:%2" : "=&v"(r) : "v"(vb), "i"(OFF) : "memory"); return r; }
; template <int H> DI void v_reads(s16x4* vf, int vb) {
;     vf[0] = tr_read<v_rd_off(0, 2 * H, 0)>(vb); vf[1] = tr_read<v_rd_off(0, 2 * H, 1)>(vb); vf[2] = tr_read<v_rd_off(0, 2 * H + 1, 0)>(vb); vf[3] = tr_read<v_rd_off(0, 2 * H + 1, 1)>(vb);
;     vf[4] = tr_read<v_rd_off(1, 2 * H, 0)>(vb); vf[5] = tr_read<v_rd_off(1, 2 * H, 1)>(vb); vf[6] = tr_read<v_rd_off(1, 2 * H + 1, 0)>(vb); vf[7] = tr_read<v_rd_off(1, 2 * H + 1, 1)>(vb);
;     vf[8] = tr_read<v_rd_off(2, 2 * H, 0)>(vb); vf[9] = tr_read<v_rd_off(2, 2 * H, 1)>(vb); vf[10] = tr_read<v_rd_off(2, 2 * H + 1, 0)>(vb); vf[11] = tr_read<v_rd_off(2, 2 * H + 1, 1)>(vb);
;     vf[12] = tr_read<v_rd_off(3, 2 * H, 0)>(vb); vf[13] = tr_read<v_rd_off(3, 2 * H, 1)>(vb); vf[14] = tr_read<v_rd_off(3, 2 * H + 1, 0)>(vb); vf[15] = tr_read<v_rd_off(3, 2 * H + 1, 1)>(vb);
; }
; DI void pv_mma(f32x16* o, const s16x4* vf, bf16x8 pa0, bf16x8 pa1) {
;     ...
; #pragma unroll
;     for (int d0 = 0; d0 < 4; ++d0) {
;         o[d0] = __builtin_amdgcn_mfma_f32_32x32x16_bf16(pa0, ATT_PK(vf[4 * d0], vf[4 * d0 + 1]), o[d0], 0, 0, 0);
;         o[d0] = __builtin_amdgcn_mfma_f32_32x32x16_bf16(pa1, ATT_PK(vf[4 * d0 + 2], vf[4 * d0 + 3]), o[d0], 0, 0, 0); }
;     ...
; }
; template <int DQK, int D0A, int D0B> DI void k_reads(bf16x8* kf, const LAS unsigned char* Ks, int half, int r32, int hi) {
; #pragma unroll
;     for (int d0 = D0A; d0 < D0B; ++d0) kf[d0 - D0A] = *(const LAS bf16x8*)(Ks + half * (32 * DQK * 2) + kswz<DQK>(r32, (d0 * 16 + hi * 8) * 2));
; }
; template <int D0A, int D0B> DI void qk_mma(f32x16& p, const bf16x8* kf, const bf16x8* qr) {
; #pragma unroll
;     for (int d0 = D0A; d0 < D0B; ++d0) {
	v_mfma_f32_32x32x16_bf16 v[64:79], v[132:135], v[80:83], 0
	v_mfma_f32_32x32x16_bf16 v[64:79], v[136:139], v[84:87], v[64:79]
	v_mfma_f32_32x32x16_bf16 v[64:79], v[140:143], v[88:91], v[64:79]
	v_mfma_f32_32x32x16_bf16 v[64:79], v[174:177], v[92:95], v[64:79]
	v_mfma_f32_32x32x16_bf16 v[64:79], v[162:165], v[96:99], v[64:79]
	v_mfma_f32_32x32x16_bf16 v[64:79], v[178:181], v[100:103], v[64:79]
	s_waitcnt lgkmcnt(0)
	v_mfma_f32_32x32x16_bf16 v[64:79], v[214:217], v[104:107], v[64:79]
	v_mfma_f32_32x32x16_bf16 v[64:79], v[218:221], v[108:111], v[64:79]
	v_mfma_f32_32x32x16_bf16 v[64:79], v[166:169], v[112:115], v[64:79]
	v_mfma_f32_32x32x16_bf16 v[64:79], v[222:225], v[116:119], v[64:79]
	v_mfma_f32_32x32x16_bf16 v[64:79], v[226:229], v[120:123], v[64:79]
	v_mfma_f32_32x32x16_bf16 v[64:79], v[170:173], v[124:127], v[64:79]
	s_setprio 0
	v_add_u32_e32 v158, 0x12000, v158
	v_add_u32_e32 v132, v158, v151
	v_add_u32_e32 v136, v158, v149
	v_add_u32_e32 v140, v158, v148
	v_add_u32_e32 v161, v158, v147
	ds_read_b128 v[132:135], v132
	ds_read_b128 v[136:139], v136
	ds_read_b128 v[140:143], v140
	ds_read_b128 v[162:165], v161
	v_add_u32_e32 v161, v158, v146
	v_add_u32_e32 v170, v158, v150
	ds_read_b128 v[166:169], v161
	ds_read_b128 v[170:173], v170
	ds_read_b64_tr_b16 v[174:175], v145 offset:0x2000
	ds_read_b64_tr_b16 v[176:177], v145 offset:0x2800
	ds_read_b64_tr_b16 v[178:179], v145 offset:0x3000
	ds_read_b64_tr_b16 v[180:181], v145 offset:0x3800
	ds_read_b64_tr_b16 v[182:183], v145 offset:0x2200
	ds_read_b64_tr_b16 v[184:185], v145 offset:0x2a00
	ds_read_b64_tr_b16 v[186:187], v145 offset:0x3200
	ds_read_b64_tr_b16 v[188:189], v145 offset:0x3a00
	ds_read_b64_tr_b16 v[190:191], v145 offset:0x2400
	ds_read_b64_tr_b16 v[192:193], v145 offset:0x2c00
	ds_read_b64_tr_b16 v[194:195], v145 offset:0x3400
	ds_read_b64_tr_b16 v[196:197], v145 offset:0x3c00
	ds_read_b64_tr_b16 v[198:199], v145 offset:0x2600
	ds_read_b64_tr_b16 v[200:201], v145 offset:0x2e00
	ds_read_b64_tr_b16 v[202:203], v145 offset:0x3600
	ds_read_b64_tr_b16 v[204:205], v145 offset:0x3e00
	s_setprio 2
	v_exp_f32_e32 v64, v64
	v_exp_f32_e32 v65, v65
	v_exp_f32_e32 v66, v66
	v_exp_f32_e32 v67, v67
	v_exp_f32_e32 v68, v68
	v_add_f32_e32 v145, 0, v64
	v_exp_f32_e32 v69, v69
	v_add_f32_e32 v145, v65, v145
	v_exp_f32_e32 v70, v70
	v_add_f32_e32 v145, v66, v145
	v_exp_f32_e32 v71, v71
	v_add_f32_e32 v145, v67, v145
	v_exp_f32_e32 v72, v72
	v_add_f32_e32 v145, v68, v145
	v_exp_f32_e32 v73, v73
	v_add_f32_e32 v145, v69, v145
	v_exp_f32_e32 v74, v74
	v_add_f32_e32 v145, v70, v145
	v_exp_f32_e32 v75, v75
	v_add_f32_e32 v145, v71, v145
	v_exp_f32_e32 v76, v76
	v_add_f32_e32 v145, v72, v145
	v_exp_f32_e32 v77, v77
	v_add_f32_e32 v145, v73, v145
	v_exp_f32_e32 v78, v78
	v_add_f32_e32 v145, v74, v145
	v_exp_f32_e32 v79, v79
	v_add_f32_e32 v145, v75, v145
	v_add_f32_e32 v145, v76, v145
	v_add_f32_e32 v145, v77, v145
	v_add_f32_e32 v145, v78, v145
	v_add_f32_e32 v145, v79, v145
	v_add_f32_e32 v161, v144, v145
	v_cvt_pk_bf16_f32 v64, v64, v65
	v_cvt_pk_bf16_f32 v65, v66, v67
	v_cvt_pk_bf16_f32 v66, v68, v69
	v_cvt_pk_bf16_f32 v67, v70, v71
	v_cvt_pk_bf16_f32 v68, v72, v73
	v_cvt_pk_bf16_f32 v69, v74, v75
	v_cvt_pk_bf16_f32 v70, v76, v77
	v_cvt_pk_bf16_f32 v71, v78, v79
	s_nop 0
	v_permlane32_swap_b32_e32 v64, v66
	v_permlane32_swap_b32_e32 v65, v67
	v_permlane32_swap_b32_e32 v68, v70
	v_permlane32_swap_b32_e32 v69, v71
	s_waitcnt lgkmcnt(0)
	v_add_u32_e32 v72, v158, v152
	v_add_u32_e32 v73, v158, v153
	ds_read_b128 v[206:209], v72
	ds_read_b128 v[210:213], v73
	v_add_u32_e32 v72, v158, v154
	v_add_u32_e32 v73, v158, v155
	ds_read_b128 v[214:217], v72
	ds_read_b128 v[218:221], v73
	v_add_u32_e32 v72, v158, v156
	v_add_u32_e32 v73, v158, v157
	ds_read_b128 v[222:225], v72
	ds_read_b128 v[226:229], v73
	s_setprio 1
	v_mfma_f32_32x32x16_bf16 v[48:63], v[64:67], v[174:177], v[48:63]
	v_mfma_f32_32x32x16_bf16 v[32:47], v[64:67], v[182:185], v[32:47]
	v_mfma_f32_32x32x16_bf16 v[16:31], v[64:67], v[190:193], v[16:31]
	v_mfma_f32_32x32x16_bf16 v[0:15], v[64:67], v[198:201], v[0:15]
	v_mfma_f32_32x32x16_bf16 v[48:63], v[68:71], v[178:181], v[48:63]
	v_mfma_f32_32x32x16_bf16 v[32:47], v[68:71], v[186:189], v[32:47]
	v_mfma_f32_32x32x16_bf16 v[16:31], v[68:71], v[194:197], v[16:31]
	v_mfma_f32_32x32x16_bf16 v[0:15], v[68:71], v[202:205], v[0:15]
	s_cmp_lt_u32 s33, 0x100
	s_cbranch_scc1 .Lstg_mla_m62_7
	s_waitcnt vmcnt(0)
	s_barrier
.Lstg_mla_m62_7:
	s_waitcnt lgkmcnt(0)
	v_mfma_f32_32x32x16_bf16 v[64:79], v[132:135], v[80:83], 0
	v_mfma_f32_32x32x16_bf16 v[64:79], v[136:139], v[84:87], v[64:79]
	v_mfma_f32_32x32x16_bf16 v[64:79], v[140:143], v[88:91], v[64:79]
	v_mfma_f32_32x32x16_bf16 v[64:79], v[162:165], v[92:95], v[64:79]
	v_mfma_f32_32x32x16_bf16 v[64:79], v[166:169], v[96:99], v[64:79]
	v_mfma_f32_32x32x16_bf16 v[64:79], v[170:173], v[100:103], v[64:79]
	s_waitcnt lgkmcnt(0)
	v_mfma_f32_32x32x16_bf16 v[64:79], v[206:209], v[104:107], v[64:79]
	v_mfma_f32_32x32x16_bf16 v[64:79], v[210:213], v[108:111], v[64:79]
	v_mfma_f32_32x32x16_bf16 v[64:79], v[214:217], v[112:115], v[64:79]
	v_mfma_f32_32x32x16_bf16 v[64:79], v[218:221], v[116:119], v[64:79]
	v_mfma_f32_32x32x16_bf16 v[64:79], v[222:225], v[120:123], v[64:79]
	v_mfma_f32_32x32x16_bf16 v[64:79], v[226:229], v[124:127], v[64:79]
	s_cmp_lt_u32 s33, 0x100
	s_cbranch_scc0 .Lstg_mla_t63_8
	s_waitcnt vmcnt(0)
	s_barrier
